# inter-chunk scan rewritten (4 waves, 2 states per lane, 8-byte loads, packed bf16x2 stores); fp8 loop s_nop removal; attention loop as v19
# speedup vs baseline: 1.0148x; 1.0047x over previous
; #define PG8_STAGE(bufoff, gbase, voff) do { _Pragma("unroll") for (int _i = 0; _i < 2; ++_i) \
;         __builtin_amdgcn_global_load_lds((const unsigned*)((const char*)(gbase) + (voff)[_i]), (PG8_LAS unsigned*)(lds + (bufoff) + ldsw + _i * 8192), 16, 0, 0); } while (0)
; #define PG8_LDA(dst, b, h) do { _Pragma("unroll") for (int m = 0; m < 4; ++m) _Pragma("unroll") for (int k = 0; k < 2; ++k) dst[m][k] = *(const PG8_LAS bf16x8*)(lds + PG8_SA(b, h) + aoff + m * 2048 + k * 1024); } while (0)
; #define PG8_LDB(dst, b, h) do { _Pragma("unroll") for (int n = 0; n < 2; ++n) _Pragma("unroll") for (int k = 0; k < 2; ++k) dst[n][k] = *(const PG8_LAS bf16x8*)(lds + PG8_SB(b, h) + boff + n * 2048 + k * 1024); } while (0)
; #define PG8_WAIT_V(n) asm volatile("s_waitcnt vmcnt(" #n ")" ::: "memory")
; #define PG8_WAIT_L(n) asm volatile("s_waitcnt lgkmcnt(" #n ")" ::: "memory")
; #define PG8_BAR __builtin_amdgcn_s_barrier()
; #define PG8_SCHED __builtin_amdgcn_sched_barrier(0)
; template <class Epi, class Sched, bool ALIGN_EPI = false, bool SP2 = false, bool FP8 = false>
; __device__ __forceinline__ void gemm_phase(PG8_LAS unsigned char* lds, const Gemm g, const Sched& S, const Epi& E) {
;     ...
;             PG8_LDB(B0, 0, 0); PG8_SCHED; PG8_LDA(At, 0, 0); PG8_STAGE(PG8_SA(1, 1), a1 + hstepA, voffA);
;             PG8_WAIT_L(8); PG8_BAR; PG8_WAIT_L(0); PG8_MMA(0, 0, At, B0); PG8_BAR; PG8_SCHED;
;             PG8_LDB(B1, 0, 1); PG8_STAGE(PG8_SB(0, 0), b2, voffB);
;             PG8_BAR; PG8_WAIT_L(0); PG8_MMA(0, 1, At, B1); PG8_BAR;
;             PG8_LDA(At, 0, 1); PG8_STAGE(PG8_SA(0, 0), a2, voffA);
;             PG8_BAR; PG8_WAIT_L(0); PG8_MMA(1, 0, At, B0); PG8_BAR; PG8_SCHED;
;             PG8_STAGE(PG8_SB(0, 1), b2 + hstepB, voffB);
;             PG8_WAIT_V(6); PG8_BAR; PG8_MMA(1, 1, At, B1); PG8_BAR;
.LBB0_218:
	ds_read_b128 v[10:13], v189
	ds_read_b128 v[14:17], v189 offset:1024
	ds_read_b128 v[2:5], v189 offset:2048
	ds_read_b128 v[6:9], v189 offset:3072
	s_add_u32 s56, s54, 0xfffe0080
	s_addc_u32 s57, s55, -1
	s_cmp_eq_u32 s33, 4
	s_cselect_b32 s69, s1, s57
	s_cselect_b32 s68, s43, s56
	s_cselect_b32 s57, s53, s96
	s_cselect_b32 s56, s94, s95
	v_lshl_add_u64 v[18:19], s[54:55], 0, v[170:171]
	s_add_i32 m0, s71, 0xc000
	ds_read_b128 v[194:197], v190
	ds_read_b128 v[198:201], v190 offset:1024
	ds_read_b128 v[202:205], v190 offset:2048
	ds_read_b128 v[206:209], v190 offset:3072
	ds_read_b128 v[210:213], v190 offset:4096
	ds_read_b128 v[214:217], v190 offset:5120
	ds_read_b128 v[218:221], v190 offset:6144
	ds_read_b128 v[222:225], v190 offset:7168
	global_load_lds_dwordx4 v[18:19], off
	v_lshl_add_u64 v[18:19], s[54:55], 0, v[172:173]
	s_add_i32 m0, s71, 0xe000
	s_nop 0
	global_load_lds_dwordx4 v[18:19], off
	s_waitcnt lgkmcnt(8)
	s_barrier
	s_waitcnt lgkmcnt(0)
	s_setprio 1
	s_waitcnt lgkmcnt(0)
	v_mfma_scale_f32_16x16x128_f8f6f4 v[150:153], v[10:17], v[194:201], v[150:153], v191, v191 op_sel_hi:[0,0,0]
	v_mfma_scale_f32_16x16x128_f8f6f4 v[146:149], v[2:9], v[194:201], v[146:149], v191, v191 op_sel_hi:[0,0,0]
	v_mfma_scale_f32_16x16x128_f8f6f4 v[142:145], v[10:17], v[202:209], v[142:145], v191, v191 op_sel_hi:[0,0,0]
	v_mfma_scale_f32_16x16x128_f8f6f4 v[138:141], v[2:9], v[202:209], v[138:141], v191, v191 op_sel_hi:[0,0,0]
	v_mfma_scale_f32_16x16x128_f8f6f4 v[126:129], v[10:17], v[210:217], v[126:129], v191, v191 op_sel_hi:[0,0,0]
	v_mfma_scale_f32_16x16x128_f8f6f4 v[122:125], v[2:9], v[210:217], v[122:125], v191, v191 op_sel_hi:[0,0,0]
	v_mfma_scale_f32_16x16x128_f8f6f4 v[110:113], v[10:17], v[218:225], v[110:113], v191, v191 op_sel_hi:[0,0,0]
	v_mfma_scale_f32_16x16x128_f8f6f4 v[106:109], v[2:9], v[218:225], v[106:109], v191, v191 op_sel_hi:[0,0,0]
	s_setprio 0
	s_barrier
	s_add_i32 s64, s86, s70
	v_lshl_add_u64 v[178:179], s[56:57], 0, v[156:157]
	s_mov_b32 m0, s64
	ds_read_b128 v[226:229], v192
	ds_read_b128 v[230:233], v192 offset:1024
	ds_read_b128 v[18:21], v192 offset:2048
	ds_read_b128 v[22:25], v192 offset:3072
	global_load_lds_dwordx4 v[178:179], off
	v_lshl_add_u64 v[180:181], s[56:57], 0, v[160:161]
	s_add_i32 m0, s64, 0x2000
	s_nop 0
	global_load_lds_dwordx4 v[180:181], off
	s_barrier
	s_waitcnt lgkmcnt(0)
	s_setprio 1
	s_waitcnt lgkmcnt(0)
	v_mfma_scale_f32_16x16x128_f8f6f4 v[134:137], v[226:233], v[194:201], v[134:137], v191, v191 op_sel_hi:[0,0,0]
	v_mfma_scale_f32_16x16x128_f8f6f4 v[130:133], v[18:25], v[194:201], v[130:133], v191, v191 op_sel_hi:[0,0,0]
	v_mfma_scale_f32_16x16x128_f8f6f4 v[118:121], v[226:233], v[202:209], v[118:121], v191, v191 op_sel_hi:[0,0,0]
	v_mfma_scale_f32_16x16x128_f8f6f4 v[114:117], v[18:25], v[202:209], v[114:117], v191, v191 op_sel_hi:[0,0,0]
	v_mfma_scale_f32_16x16x128_f8f6f4 v[102:105], v[226:233], v[210:217], v[102:105], v191, v191 op_sel_hi:[0,0,0]
	v_mfma_scale_f32_16x16x128_f8f6f4 v[98:101], v[18:25], v[210:217], v[98:101], v191, v191 op_sel_hi:[0,0,0]
	v_mfma_scale_f32_16x16x128_f8f6f4 v[94:97], v[226:233], v[218:225], v[94:97], v191, v191 op_sel_hi:[0,0,0]
	v_mfma_scale_f32_16x16x128_f8f6f4 v[90:93], v[18:25], v[218:225], v[90:93], v191, v191 op_sel_hi:[0,0,0]
	s_setprio 0
	s_mov_b32 m0, s71
	v_lshl_add_u64 v[182:183], s[68:69], 0, v[154:155]
	s_barrier
	ds_read_b128 v[194:197], v190 offset:16384
	ds_read_b128 v[198:201], v190 offset:17408
	ds_read_b128 v[202:205], v190 offset:18432
	ds_read_b128 v[206:209], v190 offset:19456
	ds_read_b128 v[210:213], v190 offset:20480
	ds_read_b128 v[214:217], v190 offset:21504
	ds_read_b128 v[218:221], v190 offset:22528
	ds_read_b128 v[222:225], v190 offset:23552
	global_load_lds_dwordx4 v[182:183], off
	v_lshl_add_u64 v[184:185], s[68:69], 0, v[158:159]
	s_mov_b32 m0, s72
	s_nop 0
	global_load_lds_dwordx4 v[184:185], off
	s_barrier
	s_waitcnt lgkmcnt(0)
	s_setprio 1
	s_waitcnt lgkmcnt(0)
	v_mfma_scale_f32_16x16x128_f8f6f4 v[86:89], v[10:17], v[194:201], v[86:89], v191, v191 op_sel_hi:[0,0,0]
	v_mfma_scale_f32_16x16x128_f8f6f4 v[82:85], v[2:9], v[194:201], v[82:85], v191, v191 op_sel_hi:[0,0,0]
	v_mfma_scale_f32_16x16x128_f8f6f4 v[78:81], v[10:17], v[202:209], v[78:81], v191, v191 op_sel_hi:[0,0,0]
	v_mfma_scale_f32_16x16x128_f8f6f4 v[74:77], v[2:9], v[202:209], v[74:77], v191, v191 op_sel_hi:[0,0,0]
	v_mfma_scale_f32_16x16x128_f8f6f4 v[62:65], v[10:17], v[210:217], v[62:65], v191, v191 op_sel_hi:[0,0,0]
	v_mfma_scale_f32_16x16x128_f8f6f4 v[58:61], v[2:9], v[210:217], v[58:61], v191, v191 op_sel_hi:[0,0,0]
	v_mfma_scale_f32_16x16x128_f8f6f4 v[46:49], v[10:17], v[218:225], v[46:49], v191, v191 op_sel_hi:[0,0,0]
	v_mfma_scale_f32_16x16x128_f8f6f4 v[42:45], v[2:9], v[218:225], v[42:45], v191, v191 op_sel_hi:[0,0,0]
	s_setprio 0
	s_barrier
	s_add_u32 vcc_lo, s56, 0x20000
	s_addc_u32 vcc_hi, s57, 0
	s_add_i32 s64, s87, s70
	v_lshl_add_u64 v[2:3], vcc, 0, v[156:157]
	s_mov_b32 m0, s64
	s_nop 0
	global_load_lds_dwordx4 v[2:3], off
	v_lshl_add_u64 v[2:3], vcc, 0, v[160:161]
	s_add_i32 m0, s64, 0x2000
	s_nop 0
	global_load_lds_dwordx4 v[2:3], off
	s_waitcnt vmcnt(6)
	s_barrier
	s_setprio 1
	v_mfma_scale_f32_16x16x128_f8f6f4 v[70:73], v[226:233], v[194:201], v[70:73], v191, v191 op_sel_hi:[0,0,0]
	v_mfma_scale_f32_16x16x128_f8f6f4 v[66:69], v[18:25], v[194:201], v[66:69], v191, v191 op_sel_hi:[0,0,0]
	v_mfma_scale_f32_16x16x128_f8f6f4 v[54:57], v[226:233], v[202:209], v[54:57], v191, v191 op_sel_hi:[0,0,0]
	v_mfma_scale_f32_16x16x128_f8f6f4 v[50:53], v[18:25], v[202:209], v[50:53], v191, v191 op_sel_hi:[0,0,0]
	v_mfma_scale_f32_16x16x128_f8f6f4 v[38:41], v[226:233], v[210:217], v[38:41], v191, v191 op_sel_hi:[0,0,0]
	v_mfma_scale_f32_16x16x128_f8f6f4 v[34:37], v[18:25], v[210:217], v[34:37], v191, v191 op_sel_hi:[0,0,0]
	v_mfma_scale_f32_16x16x128_f8f6f4 v[30:33], v[226:233], v[218:225], v[30:33], v191, v191 op_sel_hi:[0,0,0]
	v_mfma_scale_f32_16x16x128_f8f6f4 v[26:29], v[18:25], v[218:225], v[26:29], v191, v191 op_sel_hi:[0,0,0]
	s_setprio 0
	s_add_i32 s64, 0, 0x18000
	v_add_u32_e32 v14, s64, v163
	s_barrier
; #define PG8_STAGE(bufoff, gbase, voff) do { _Pragma("unroll") for (int _i = 0; _i < 2; ++_i) \
;         __builtin_amdgcn_global_load_lds((const unsigned*)((const char*)(gbase) + (voff)[_i]), (PG8_LAS unsigned*)(lds + (bufoff) + ldsw + _i * 8192), 16, 0, 0); } while (0)
; #define PG8_LDA(dst, b, h) do { _Pragma("unroll") for (int m = 0; m < 4; ++m) _Pragma("unroll") for (int k = 0; k < 2; ++k) dst[m][k] = *(const PG8_LAS bf16x8*)(lds + PG8_SA(b, h) + aoff + m * 2048 + k * 1024); } while (0)
; #define PG8_LDB(dst, b, h) do { _Pragma("unroll") for (int n = 0; n < 2; ++n) _Pragma("unroll") for (int k = 0; k < 2; ++k) dst[n][k] = *(const PG8_LAS bf16x8*)(lds + PG8_SB(b, h) + boff + n * 2048 + k * 1024); } while (0)
; #define PG8_WAIT_V(n) asm volatile("s_waitcnt vmcnt(" #n ")" ::: "memory")
; #define PG8_WAIT_L(n) asm volatile("s_waitcnt lgkmcnt(" #n ")" ::: "memory")
; #define PG8_BAR __builtin_amdgcn_s_barrier()
; #define PG8_SCHED __builtin_amdgcn_sched_barrier(0)
; template <class Epi, class Sched, bool ALIGN_EPI = false, bool SP2 = false, bool FP8 = false>
; __device__ __forceinline__ void gemm_phase(PG8_LAS unsigned char* lds, const Gemm g, const Sched& S, const Epi& E) {
;     ...
;             PG8_LDB(B0, 1, 0); PG8_SCHED; PG8_LDA(At, 1, 0); PG8_STAGE(PG8_SA(0, 1), a2 + hstepA, voffA);
;             PG8_WAIT_L(8); PG8_BAR; PG8_WAIT_L(0); PG8_MMA(0, 0, At, B0); PG8_BAR; PG8_SCHED;
;             PG8_LDB(B1, 1, 1); PG8_STAGE(PG8_SB(1, 0), b3, voffB);
;             PG8_BAR; PG8_WAIT_L(0); PG8_MMA(0, 1, At, B1); PG8_BAR;
;             PG8_LDA(At, 1, 1); PG8_STAGE(PG8_SA(1, 0), a3, voffA);
;             PG8_BAR; PG8_WAIT_L(0); PG8_MMA(1, 0, At, B0); PG8_BAR; PG8_SCHED;
;             PG8_STAGE(PG8_SB(1, 1), b3 + hstepB, voffB);
;             PG8_WAIT_V(6); PG8_BAR; PG8_MMA(1, 1, At, B1); PG8_BAR;
	ds_read_b128 v[2:5], v14
	ds_read_b128 v[6:9], v14 offset:1024
	ds_read_b128 v[10:13], v14 offset:2048
	ds_read_b128 v[14:17], v14 offset:3072
	s_add_u32 s68, s68, 0x20000
	s_addc_u32 s69, s69, 0
	s_mov_b32 m0, s73
	v_lshl_add_u64 v[186:187], s[68:69], 0, v[154:155]
	ds_read_b128 v[18:21], v190 offset:32768
	ds_read_b128 v[22:25], v190 offset:33792
	ds_read_b128 v[194:197], v190 offset:34816
	ds_read_b128 v[198:201], v190 offset:35840
	ds_read_b128 v[202:205], v190 offset:36864
	ds_read_b128 v[206:209], v190 offset:37888
	ds_read_b128 v[210:213], v190 offset:38912
	ds_read_b128 v[214:217], v190 offset:39936
	global_load_lds_dwordx4 v[186:187], off
	v_lshl_add_u64 v[186:187], s[68:69], 0, v[158:159]
	s_mov_b32 m0, s76
	s_nop 0
	global_load_lds_dwordx4 v[186:187], off
	s_waitcnt lgkmcnt(8)
	s_barrier
	s_waitcnt lgkmcnt(0)
	s_setprio 1
	s_waitcnt lgkmcnt(0)
	v_mfma_scale_f32_16x16x128_f8f6f4 v[150:153], v[2:9], v[18:25], v[150:153], v191, v191 op_sel_hi:[0,0,0]
	v_mfma_scale_f32_16x16x128_f8f6f4 v[146:149], v[10:17], v[18:25], v[146:149], v191, v191 op_sel_hi:[0,0,0]
	v_mfma_scale_f32_16x16x128_f8f6f4 v[142:145], v[2:9], v[194:201], v[142:145], v191, v191 op_sel_hi:[0,0,0]
	v_mfma_scale_f32_16x16x128_f8f6f4 v[138:141], v[10:17], v[194:201], v[138:141], v191, v191 op_sel_hi:[0,0,0]
	v_mfma_scale_f32_16x16x128_f8f6f4 v[126:129], v[2:9], v[202:209], v[126:129], v191, v191 op_sel_hi:[0,0,0]
	v_mfma_scale_f32_16x16x128_f8f6f4 v[122:125], v[10:17], v[202:209], v[122:125], v191, v191 op_sel_hi:[0,0,0]
	v_mfma_scale_f32_16x16x128_f8f6f4 v[110:113], v[2:9], v[210:217], v[110:113], v191, v191 op_sel_hi:[0,0,0]
	v_mfma_scale_f32_16x16x128_f8f6f4 v[106:109], v[10:17], v[210:217], v[106:109], v191, v191 op_sel_hi:[0,0,0]
	s_setprio 0
	s_barrier
	s_add_i32 s65, 0, 0x1c000
	s_add_i32 s64, s64, s70
	v_add_u32_e32 v175, s65, v163
	v_lshl_add_u64 v[178:179], v[178:179], 0, s[24:25]
	s_mov_b32 m0, s64
	ds_read_b128 v[218:221], v175
	ds_read_b128 v[222:225], v175 offset:1024
	ds_read_b128 v[226:229], v175 offset:2048
	ds_read_b128 v[230:233], v175 offset:3072
	global_load_lds_dwordx4 v[178:179], off
	v_lshl_add_u64 v[178:179], v[180:181], 0, s[24:25]
	s_add_i32 m0, s64, 0x2000
	s_nop 0
	global_load_lds_dwordx4 v[178:179], off
	s_barrier
	s_waitcnt lgkmcnt(0)
	s_setprio 1
	s_waitcnt lgkmcnt(0)
	v_mfma_scale_f32_16x16x128_f8f6f4 v[134:137], v[218:225], v[18:25], v[134:137], v191, v191 op_sel_hi:[0,0,0]
	v_mfma_scale_f32_16x16x128_f8f6f4 v[130:133], v[226:233], v[18:25], v[130:133], v191, v191 op_sel_hi:[0,0,0]
	v_mfma_scale_f32_16x16x128_f8f6f4 v[118:121], v[218:225], v[194:201], v[118:121], v191, v191 op_sel_hi:[0,0,0]
	v_mfma_scale_f32_16x16x128_f8f6f4 v[114:117], v[226:233], v[194:201], v[114:117], v191, v191 op_sel_hi:[0,0,0]
	v_mfma_scale_f32_16x16x128_f8f6f4 v[102:105], v[218:225], v[202:209], v[102:105], v191, v191 op_sel_hi:[0,0,0]
	v_mfma_scale_f32_16x16x128_f8f6f4 v[98:101], v[226:233], v[202:209], v[98:101], v191, v191 op_sel_hi:[0,0,0]
	v_mfma_scale_f32_16x16x128_f8f6f4 v[94:97], v[218:225], v[210:217], v[94:97], v191, v191 op_sel_hi:[0,0,0]
	v_mfma_scale_f32_16x16x128_f8f6f4 v[90:93], v[226:233], v[210:217], v[90:93], v191, v191 op_sel_hi:[0,0,0]
	s_setprio 0
	s_mov_b32 m0, s82
	v_lshl_add_u64 v[178:179], v[182:183], 0, s[24:25]
	s_barrier
	ds_read_b128 v[18:21], v190 offset:49152
	ds_read_b128 v[22:25], v190 offset:50176
	ds_read_b128 v[194:197], v190 offset:51200
	ds_read_b128 v[198:201], v190 offset:52224
	ds_read_b128 v[202:205], v190 offset:53248
	ds_read_b128 v[206:209], v190 offset:54272
	ds_read_b128 v[210:213], v190 offset:55296
	ds_read_b128 v[214:217], v190 offset:56320
	global_load_lds_dwordx4 v[178:179], off
	v_lshl_add_u64 v[178:179], v[184:185], 0, s[24:25]
	s_mov_b32 m0, s83
	s_nop 0
	global_load_lds_dwordx4 v[178:179], off
	s_barrier
	s_waitcnt lgkmcnt(0)
	s_setprio 1
	s_waitcnt lgkmcnt(0)
	v_mfma_scale_f32_16x16x128_f8f6f4 v[86:89], v[2:9], v[18:25], v[86:89], v191, v191 op_sel_hi:[0,0,0]
	v_mfma_scale_f32_16x16x128_f8f6f4 v[82:85], v[10:17], v[18:25], v[82:85], v191, v191 op_sel_hi:[0,0,0]
	v_mfma_scale_f32_16x16x128_f8f6f4 v[78:81], v[2:9], v[194:201], v[78:81], v191, v191 op_sel_hi:[0,0,0]
	v_mfma_scale_f32_16x16x128_f8f6f4 v[74:77], v[10:17], v[194:201], v[74:77], v191, v191 op_sel_hi:[0,0,0]
	v_mfma_scale_f32_16x16x128_f8f6f4 v[62:65], v[2:9], v[202:209], v[62:65], v191, v191 op_sel_hi:[0,0,0]
	v_mfma_scale_f32_16x16x128_f8f6f4 v[58:61], v[10:17], v[202:209], v[58:61], v191, v191 op_sel_hi:[0,0,0]
	v_mfma_scale_f32_16x16x128_f8f6f4 v[46:49], v[2:9], v[210:217], v[46:49], v191, v191 op_sel_hi:[0,0,0]
	v_mfma_scale_f32_16x16x128_f8f6f4 v[42:45], v[10:17], v[210:217], v[42:45], v191, v191 op_sel_hi:[0,0,0]
	s_setprio 0
	s_barrier
	s_add_u32 s56, s56, 0x20080
	s_addc_u32 s57, s57, 0
	s_add_i32 s64, s65, s70
	v_lshl_add_u64 v[2:3], s[56:57], 0, v[156:157]
	s_mov_b32 m0, s64
	s_nop 0
	global_load_lds_dwordx4 v[2:3], off
	v_lshl_add_u64 v[2:3], s[56:57], 0, v[160:161]
	s_add_i32 m0, s64, 0x2000
	s_nop 0
	global_load_lds_dwordx4 v[2:3], off
	s_waitcnt vmcnt(6)
	s_barrier
	s_setprio 1
	v_mfma_scale_f32_16x16x128_f8f6f4 v[70:73], v[218:225], v[18:25], v[70:73], v191, v191 op_sel_hi:[0,0,0]
	v_mfma_scale_f32_16x16x128_f8f6f4 v[66:69], v[226:233], v[18:25], v[66:69], v191, v191 op_sel_hi:[0,0,0]
	v_mfma_scale_f32_16x16x128_f8f6f4 v[54:57], v[218:225], v[194:201], v[54:57], v191, v191 op_sel_hi:[0,0,0]
	v_mfma_scale_f32_16x16x128_f8f6f4 v[50:53], v[226:233], v[194:201], v[50:53], v191, v191 op_sel_hi:[0,0,0]
	v_mfma_scale_f32_16x16x128_f8f6f4 v[38:41], v[218:225], v[202:209], v[38:41], v191, v191 op_sel_hi:[0,0,0]
	v_mfma_scale_f32_16x16x128_f8f6f4 v[34:37], v[226:233], v[202:209], v[34:37], v191, v191 op_sel_hi:[0,0,0]
	v_mfma_scale_f32_16x16x128_f8f6f4 v[30:33], v[218:225], v[210:217], v[30:33], v191, v191 op_sel_hi:[0,0,0]
	v_mfma_scale_f32_16x16x128_f8f6f4 v[26:29], v[226:233], v[210:217], v[26:29], v191, v191 op_sel_hi:[0,0,0]
	s_setprio 0
	s_add_i32 s33, s33, 2
	s_add_u32 s54, s54, 0x100
	s_addc_u32 s55, s55, 0
	s_add_u32 s95, s95, 0x100
	s_addc_u32 s96, s96, 0
	s_cmp_gt_u32 s33, 5
	s_barrier
	s_cbranch_scc0 .LBB0_218
	s_and_b64 vcc, exec, s[26:27]
	s_cbranch_vccz .LBB0_221
	s_barrier

; #define PG8_STAGE(bufoff, gbase, voff) do { _Pragma("unroll") for (int _i = 0; _i < 2; ++_i) \
;         __builtin_amdgcn_global_load_lds((const unsigned*)((const char*)(gbase) + (voff)[_i]), (PG8_LAS unsigned*)(lds + (bufoff) + ldsw + _i * 8192), 16, 0, 0); } while (0)
; #define PG8_LDA(dst, b, h) do { _Pragma("unroll") for (int m = 0; m < 4; ++m) _Pragma("unroll") for (int k = 0; k < 2; ++k) dst[m][k] = *(const PG8_LAS bf16x8*)(lds + PG8_SA(b, h) + aoff + m * 2048 + k * 1024); } while (0)
; #define PG8_LDB(dst, b, h) do { _Pragma("unroll") for (int n = 0; n < 2; ++n) _Pragma("unroll") for (int k = 0; k < 2; ++k) dst[n][k] = *(const PG8_LAS bf16x8*)(lds + PG8_SB(b, h) + boff + n * 2048 + k * 1024); } while (0)
; #define PG8_WAIT_V(n) asm volatile("s_waitcnt vmcnt(" #n ")" ::: "memory")
; #define PG8_WAIT_L(n) asm volatile("s_waitcnt lgkmcnt(" #n ")" ::: "memory")
; #define PG8_BAR __builtin_amdgcn_s_barrier()
; #define PG8_SCHED __builtin_amdgcn_sched_barrier(0)
; template <class Epi, class Sched, bool ALIGN_EPI = false, bool SP2 = false, bool FP8 = false>
; __device__ __forceinline__ void gemm_phase(PG8_LAS unsigned char* lds, const Gemm g, const Sched& S, const Epi& E) {
;     ...
;             PG8_LDB(B0, 0, 0); PG8_SCHED; PG8_LDA(At, 0, 0); PG8_STAGE(PG8_SA(1, 1), a1 + hstepA, voffA);
;             PG8_WAIT_L(8); PG8_BAR; PG8_WAIT_L(0); PG8_MMA(0, 0, At, B0); PG8_BAR; PG8_SCHED;
;             PG8_LDB(B1, 0, 1); PG8_STAGE(PG8_SB(0, 0), b2, voffB);
;             PG8_BAR; PG8_WAIT_L(0); PG8_MMA(0, 1, At, B1); PG8_BAR;
;             PG8_LDA(At, 0, 1); PG8_STAGE(PG8_SA(0, 0), a2, voffA);
;             PG8_BAR; PG8_WAIT_L(0); PG8_MMA(1, 0, At, B0); PG8_BAR; PG8_SCHED;
;             PG8_STAGE(PG8_SB(0, 1), b2 + hstepB, voffB);
;             PG8_WAIT_V(6); PG8_BAR; PG8_MMA(1, 1, At, B1); PG8_BAR;
.LBB0_330:
	ds_read_b128 v[10:13], v191
	ds_read_b128 v[14:17], v191 offset:1024
	ds_read_b128 v[2:5], v191 offset:2048
	ds_read_b128 v[6:9], v191 offset:3072
	s_add_u32 s64, s68, 0xfffe0080
	s_addc_u32 s65, s69, -1
	s_cmp_eq_u32 s80, 4
	s_cselect_b32 s73, s1, s65
	s_cselect_b32 s72, s47, s64
	s_cselect_b32 s71, s49, s33
	s_cselect_b32 s70, vcc_lo, vcc_hi
	v_lshl_add_u64 v[18:19], s[68:69], 0, v[170:171]
	s_add_i32 m0, s67, 0xc000
	ds_read_b128 v[196:199], v192
	ds_read_b128 v[200:203], v192 offset:1024
	ds_read_b128 v[204:207], v192 offset:2048
	ds_read_b128 v[208:211], v192 offset:3072
	ds_read_b128 v[212:215], v192 offset:4096
	ds_read_b128 v[216:219], v192 offset:5120
	ds_read_b128 v[220:223], v192 offset:6144
	ds_read_b128 v[224:227], v192 offset:7168
	global_load_lds_dwordx4 v[18:19], off
	v_lshl_add_u64 v[18:19], s[68:69], 0, v[172:173]
	s_add_i32 m0, s67, 0xe000
	s_nop 0
	global_load_lds_dwordx4 v[18:19], off
	s_waitcnt lgkmcnt(8)
	s_barrier
	s_waitcnt lgkmcnt(0)
	s_setprio 1
	s_waitcnt lgkmcnt(0)
	v_mfma_scale_f32_16x16x128_f8f6f4 v[150:153], v[10:17], v[196:203], v[150:153], v193, v193 op_sel_hi:[0,0,0]
	v_mfma_scale_f32_16x16x128_f8f6f4 v[146:149], v[2:9], v[196:203], v[146:149], v193, v193 op_sel_hi:[0,0,0]
	v_mfma_scale_f32_16x16x128_f8f6f4 v[134:137], v[10:17], v[204:211], v[134:137], v193, v193 op_sel_hi:[0,0,0]
	v_mfma_scale_f32_16x16x128_f8f6f4 v[130:133], v[2:9], v[204:211], v[130:133], v193, v193 op_sel_hi:[0,0,0]
	v_mfma_scale_f32_16x16x128_f8f6f4 v[118:121], v[10:17], v[212:219], v[118:121], v193, v193 op_sel_hi:[0,0,0]
	v_mfma_scale_f32_16x16x128_f8f6f4 v[114:117], v[2:9], v[212:219], v[114:117], v193, v193 op_sel_hi:[0,0,0]
	v_mfma_scale_f32_16x16x128_f8f6f4 v[102:105], v[10:17], v[220:227], v[102:105], v193, v193 op_sel_hi:[0,0,0]
	v_mfma_scale_f32_16x16x128_f8f6f4 v[98:101], v[2:9], v[220:227], v[98:101], v193, v193 op_sel_hi:[0,0,0]
	s_setprio 0
	s_barrier
	s_add_i32 s64, s94, s84
	v_lshl_add_u64 v[178:179], s[70:71], 0, v[156:157]
	s_mov_b32 m0, s64
	ds_read_b128 v[228:231], v194
	ds_read_b128 v[232:235], v194 offset:1024
	ds_read_b128 v[18:21], v194 offset:2048
	ds_read_b128 v[22:25], v194 offset:3072
	global_load_lds_dwordx4 v[178:179], off
	v_lshl_add_u64 v[180:181], s[70:71], 0, v[160:161]
	s_add_i32 m0, s64, 0x2000
	s_nop 0
	global_load_lds_dwordx4 v[180:181], off
	s_barrier
	s_waitcnt lgkmcnt(0)
	s_setprio 1
	s_waitcnt lgkmcnt(0)
	v_mfma_scale_f32_16x16x128_f8f6f4 v[142:145], v[228:235], v[196:203], v[142:145], v193, v193 op_sel_hi:[0,0,0]
	v_mfma_scale_f32_16x16x128_f8f6f4 v[138:141], v[18:25], v[196:203], v[138:141], v193, v193 op_sel_hi:[0,0,0]
	v_mfma_scale_f32_16x16x128_f8f6f4 v[126:129], v[228:235], v[204:211], v[126:129], v193, v193 op_sel_hi:[0,0,0]
	v_mfma_scale_f32_16x16x128_f8f6f4 v[122:125], v[18:25], v[204:211], v[122:125], v193, v193 op_sel_hi:[0,0,0]
	v_mfma_scale_f32_16x16x128_f8f6f4 v[110:113], v[228:235], v[212:219], v[110:113], v193, v193 op_sel_hi:[0,0,0]
	v_mfma_scale_f32_16x16x128_f8f6f4 v[106:109], v[18:25], v[212:219], v[106:109], v193, v193 op_sel_hi:[0,0,0]
	v_mfma_scale_f32_16x16x128_f8f6f4 v[94:97], v[228:235], v[220:227], v[94:97], v193, v193 op_sel_hi:[0,0,0]
	v_mfma_scale_f32_16x16x128_f8f6f4 v[90:93], v[18:25], v[220:227], v[90:93], v193, v193 op_sel_hi:[0,0,0]
	s_setprio 0
	s_mov_b32 m0, s67
	v_lshl_add_u64 v[182:183], s[72:73], 0, v[154:155]
	s_barrier
	ds_read_b128 v[196:199], v192 offset:16384
	ds_read_b128 v[200:203], v192 offset:17408
	ds_read_b128 v[204:207], v192 offset:18432
	ds_read_b128 v[208:211], v192 offset:19456
	ds_read_b128 v[212:215], v192 offset:20480
	ds_read_b128 v[216:219], v192 offset:21504
	ds_read_b128 v[220:223], v192 offset:22528
	ds_read_b128 v[224:227], v192 offset:23552
	global_load_lds_dwordx4 v[182:183], off
	v_lshl_add_u64 v[184:185], s[72:73], 0, v[158:159]
	s_mov_b32 m0, s85
	s_nop 0
	global_load_lds_dwordx4 v[184:185], off
	s_barrier
	s_waitcnt lgkmcnt(0)
	s_setprio 1
	s_waitcnt lgkmcnt(0)
	v_mfma_scale_f32_16x16x128_f8f6f4 v[86:89], v[10:17], v[196:203], v[86:89], v193, v193 op_sel_hi:[0,0,0]
	v_mfma_scale_f32_16x16x128_f8f6f4 v[82:85], v[2:9], v[196:203], v[82:85], v193, v193 op_sel_hi:[0,0,0]
	v_mfma_scale_f32_16x16x128_f8f6f4 v[70:73], v[10:17], v[204:211], v[70:73], v193, v193 op_sel_hi:[0,0,0]
	v_mfma_scale_f32_16x16x128_f8f6f4 v[66:69], v[2:9], v[204:211], v[66:69], v193, v193 op_sel_hi:[0,0,0]
	v_mfma_scale_f32_16x16x128_f8f6f4 v[54:57], v[10:17], v[212:219], v[54:57], v193, v193 op_sel_hi:[0,0,0]
	v_mfma_scale_f32_16x16x128_f8f6f4 v[50:53], v[2:9], v[212:219], v[50:53], v193, v193 op_sel_hi:[0,0,0]
	v_mfma_scale_f32_16x16x128_f8f6f4 v[38:41], v[10:17], v[220:227], v[38:41], v193, v193 op_sel_hi:[0,0,0]
	v_mfma_scale_f32_16x16x128_f8f6f4 v[34:37], v[2:9], v[220:227], v[34:37], v193, v193 op_sel_hi:[0,0,0]
	s_setprio 0
	s_barrier
	s_add_u32 s64, s70, 0x20000
	s_addc_u32 s65, s71, 0
	s_add_i32 s43, s95, s84
	v_lshl_add_u64 v[2:3], s[64:65], 0, v[156:157]
	s_mov_b32 m0, s43
	s_nop 0
	global_load_lds_dwordx4 v[2:3], off
	v_lshl_add_u64 v[2:3], s[64:65], 0, v[160:161]
	s_add_i32 m0, s43, 0x2000
	s_nop 0
	global_load_lds_dwordx4 v[2:3], off
	s_waitcnt vmcnt(6)
	s_barrier
; #define PG8_STAGE(bufoff, gbase, voff) do { _Pragma("unroll") for (int _i = 0; _i < 2; ++_i) \
;         __builtin_amdgcn_global_load_lds((const unsigned*)((const char*)(gbase) + (voff)[_i]), (PG8_LAS unsigned*)(lds + (bufoff) + ldsw + _i * 8192), 16, 0, 0); } while (0)
; #define PG8_LDA(dst, b, h) do { _Pragma("unroll") for (int m = 0; m < 4; ++m) _Pragma("unroll") for (int k = 0; k < 2; ++k) dst[m][k] = *(const PG8_LAS bf16x8*)(lds + PG8_SA(b, h) + aoff + m * 2048 + k * 1024); } while (0)
; #define PG8_LDB(dst, b, h) do { _Pragma("unroll") for (int n = 0; n < 2; ++n) _Pragma("unroll") for (int k = 0; k < 2; ++k) dst[n][k] = *(const PG8_LAS bf16x8*)(lds + PG8_SB(b, h) + boff + n * 2048 + k * 1024); } while (0)
; #define PG8_WAIT_V(n) asm volatile("s_waitcnt vmcnt(" #n ")" ::: "memory")
; #define PG8_WAIT_L(n) asm volatile("s_waitcnt lgkmcnt(" #n ")" ::: "memory")
; #define PG8_BAR __builtin_amdgcn_s_barrier()
; #define PG8_SCHED __builtin_amdgcn_sched_barrier(0)
; template <class Epi, class Sched, bool ALIGN_EPI = false, bool SP2 = false, bool FP8 = false>
; __device__ __forceinline__ void gemm_phase(PG8_LAS unsigned char* lds, const Gemm g, const Sched& S, const Epi& E) {
;     ...
;             PG8_WAIT_V(6); PG8_BAR; PG8_MMA(1, 1, At, B1); PG8_BAR;
;             PG8_LDB(B0, 1, 0); PG8_SCHED; PG8_LDA(At, 1, 0); PG8_STAGE(PG8_SA(0, 1), a2 + hstepA, voffA);
;             PG8_WAIT_L(8); PG8_BAR; PG8_WAIT_L(0); PG8_MMA(0, 0, At, B0); PG8_BAR; PG8_SCHED;
;             PG8_LDB(B1, 1, 1); PG8_STAGE(PG8_SB(1, 0), b3, voffB);
;             PG8_BAR; PG8_WAIT_L(0); PG8_MMA(0, 1, At, B1); PG8_BAR;
	s_setprio 1
	v_mfma_scale_f32_16x16x128_f8f6f4 v[78:81], v[228:235], v[196:203], v[78:81], v193, v193 op_sel_hi:[0,0,0]
	v_mfma_scale_f32_16x16x128_f8f6f4 v[74:77], v[18:25], v[196:203], v[74:77], v193, v193 op_sel_hi:[0,0,0]
	v_mfma_scale_f32_16x16x128_f8f6f4 v[62:65], v[228:235], v[204:211], v[62:65], v193, v193 op_sel_hi:[0,0,0]
	v_mfma_scale_f32_16x16x128_f8f6f4 v[58:61], v[18:25], v[204:211], v[58:61], v193, v193 op_sel_hi:[0,0,0]
	v_mfma_scale_f32_16x16x128_f8f6f4 v[46:49], v[228:235], v[212:219], v[46:49], v193, v193 op_sel_hi:[0,0,0]
	v_mfma_scale_f32_16x16x128_f8f6f4 v[42:45], v[18:25], v[212:219], v[42:45], v193, v193 op_sel_hi:[0,0,0]
	v_mfma_scale_f32_16x16x128_f8f6f4 v[30:33], v[228:235], v[220:227], v[30:33], v193, v193 op_sel_hi:[0,0,0]
	v_mfma_scale_f32_16x16x128_f8f6f4 v[26:29], v[18:25], v[220:227], v[26:29], v193, v193 op_sel_hi:[0,0,0]
	s_setprio 0
	s_add_i32 s43, 0, 0x18000
	v_add_u32_e32 v14, s43, v165
	s_barrier
	ds_read_b128 v[2:5], v14
	ds_read_b128 v[6:9], v14 offset:1024
	ds_read_b128 v[10:13], v14 offset:2048
	ds_read_b128 v[14:17], v14 offset:3072
	s_add_u32 s64, s72, 0x20000
	s_addc_u32 s65, s73, 0
	s_mov_b32 m0, s86
	v_lshl_add_u64 v[186:187], s[64:65], 0, v[154:155]
	ds_read_b128 v[18:21], v192 offset:32768
	ds_read_b128 v[22:25], v192 offset:33792
	ds_read_b128 v[196:199], v192 offset:34816
	ds_read_b128 v[200:203], v192 offset:35840
	ds_read_b128 v[204:207], v192 offset:36864
	ds_read_b128 v[208:211], v192 offset:37888
	ds_read_b128 v[212:215], v192 offset:38912
	ds_read_b128 v[216:219], v192 offset:39936
	global_load_lds_dwordx4 v[186:187], off
	v_lshl_add_u64 v[186:187], s[64:65], 0, v[158:159]
	s_mov_b32 m0, s87
	s_nop 0
	global_load_lds_dwordx4 v[186:187], off
	s_waitcnt lgkmcnt(8)
	s_barrier
	s_waitcnt lgkmcnt(0)
	s_setprio 1
	s_waitcnt lgkmcnt(0)
	v_mfma_scale_f32_16x16x128_f8f6f4 v[150:153], v[2:9], v[18:25], v[150:153], v193, v193 op_sel_hi:[0,0,0]
	v_mfma_scale_f32_16x16x128_f8f6f4 v[146:149], v[10:17], v[18:25], v[146:149], v193, v193 op_sel_hi:[0,0,0]
	v_mfma_scale_f32_16x16x128_f8f6f4 v[134:137], v[2:9], v[196:203], v[134:137], v193, v193 op_sel_hi:[0,0,0]
	v_mfma_scale_f32_16x16x128_f8f6f4 v[130:133], v[10:17], v[196:203], v[130:133], v193, v193 op_sel_hi:[0,0,0]
	v_mfma_scale_f32_16x16x128_f8f6f4 v[118:121], v[2:9], v[204:211], v[118:121], v193, v193 op_sel_hi:[0,0,0]
	v_mfma_scale_f32_16x16x128_f8f6f4 v[114:117], v[10:17], v[204:211], v[114:117], v193, v193 op_sel_hi:[0,0,0]
	v_mfma_scale_f32_16x16x128_f8f6f4 v[102:105], v[2:9], v[212:219], v[102:105], v193, v193 op_sel_hi:[0,0,0]
	v_mfma_scale_f32_16x16x128_f8f6f4 v[98:101], v[10:17], v[212:219], v[98:101], v193, v193 op_sel_hi:[0,0,0]
	s_setprio 0
	s_barrier
	s_add_i32 s72, 0, 0x1c000
	s_add_i32 s43, s43, s84
	v_add_u32_e32 v175, s72, v165
	v_lshl_add_u64 v[178:179], v[178:179], 0, s[36:37]
	s_mov_b32 m0, s43
	ds_read_b128 v[220:223], v175
	ds_read_b128 v[224:227], v175 offset:1024
	ds_read_b128 v[228:231], v175 offset:2048
	ds_read_b128 v[232:235], v175 offset:3072
	global_load_lds_dwordx4 v[178:179], off
	v_lshl_add_u64 v[178:179], v[180:181], 0, s[36:37]
	s_add_i32 m0, s43, 0x2000
	s_nop 0
	global_load_lds_dwordx4 v[178:179], off
	s_barrier
; #define PG8_STAGE(bufoff, gbase, voff) do { _Pragma("unroll") for (int _i = 0; _i < 2; ++_i) \
;         __builtin_amdgcn_global_load_lds((const unsigned*)((const char*)(gbase) + (voff)[_i]), (PG8_LAS unsigned*)(lds + (bufoff) + ldsw + _i * 8192), 16, 0, 0); } while (0)
; #define PG8_LDA(dst, b, h) do { _Pragma("unroll") for (int m = 0; m < 4; ++m) _Pragma("unroll") for (int k = 0; k < 2; ++k) dst[m][k] = *(const PG8_LAS bf16x8*)(lds + PG8_SA(b, h) + aoff + m * 2048 + k * 1024); } while (0)
; #define PG8_WAIT_V(n) asm volatile("s_waitcnt vmcnt(" #n ")" ::: "memory")
; #define PG8_WAIT_L(n) asm volatile("s_waitcnt lgkmcnt(" #n ")" ::: "memory")
; #define PG8_BAR __builtin_amdgcn_s_barrier()
; #define PG8_SCHED __builtin_amdgcn_sched_barrier(0)
; template <class Epi, class Sched, bool ALIGN_EPI = false, bool SP2 = false, bool FP8 = false>
; __device__ __forceinline__ void gemm_phase(PG8_LAS unsigned char* lds, const Gemm g, const Sched& S, const Epi& E) {
;     ...
;             PG8_BAR; PG8_WAIT_L(0); PG8_MMA(0, 1, At, B1); PG8_BAR;
;             PG8_LDA(At, 1, 1); PG8_STAGE(PG8_SA(1, 0), a3, voffA);
;             PG8_BAR; PG8_WAIT_L(0); PG8_MMA(1, 0, At, B0); PG8_BAR; PG8_SCHED;
;             PG8_STAGE(PG8_SB(1, 1), b3 + hstepB, voffB);
;             PG8_WAIT_V(6); PG8_BAR; PG8_MMA(1, 1, At, B1); PG8_BAR;
	s_waitcnt lgkmcnt(0)
	s_setprio 1
	s_waitcnt lgkmcnt(0)
	v_mfma_scale_f32_16x16x128_f8f6f4 v[142:145], v[220:227], v[18:25], v[142:145], v193, v193 op_sel_hi:[0,0,0]
	v_mfma_scale_f32_16x16x128_f8f6f4 v[138:141], v[228:235], v[18:25], v[138:141], v193, v193 op_sel_hi:[0,0,0]
	v_mfma_scale_f32_16x16x128_f8f6f4 v[126:129], v[220:227], v[196:203], v[126:129], v193, v193 op_sel_hi:[0,0,0]
	v_mfma_scale_f32_16x16x128_f8f6f4 v[122:125], v[228:235], v[196:203], v[122:125], v193, v193 op_sel_hi:[0,0,0]
	v_mfma_scale_f32_16x16x128_f8f6f4 v[110:113], v[220:227], v[204:211], v[110:113], v193, v193 op_sel_hi:[0,0,0]
	v_mfma_scale_f32_16x16x128_f8f6f4 v[106:109], v[228:235], v[204:211], v[106:109], v193, v193 op_sel_hi:[0,0,0]
	v_mfma_scale_f32_16x16x128_f8f6f4 v[94:97], v[220:227], v[212:219], v[94:97], v193, v193 op_sel_hi:[0,0,0]
	v_mfma_scale_f32_16x16x128_f8f6f4 v[90:93], v[228:235], v[212:219], v[90:93], v193, v193 op_sel_hi:[0,0,0]
	s_setprio 0
	s_mov_b32 m0, s90
	v_lshl_add_u64 v[178:179], v[182:183], 0, s[36:37]
	s_barrier
	ds_read_b128 v[18:21], v192 offset:49152
	ds_read_b128 v[22:25], v192 offset:50176
	ds_read_b128 v[196:199], v192 offset:51200
	ds_read_b128 v[200:203], v192 offset:52224
	ds_read_b128 v[204:207], v192 offset:53248
	ds_read_b128 v[208:211], v192 offset:54272
	ds_read_b128 v[212:215], v192 offset:55296
	ds_read_b128 v[216:219], v192 offset:56320
	global_load_lds_dwordx4 v[178:179], off
	v_lshl_add_u64 v[178:179], v[184:185], 0, s[36:37]
	s_mov_b32 m0, s91
	s_nop 0
	global_load_lds_dwordx4 v[178:179], off
	s_barrier
	s_waitcnt lgkmcnt(0)
	s_setprio 1
	s_waitcnt lgkmcnt(0)
	v_mfma_scale_f32_16x16x128_f8f6f4 v[86:89], v[2:9], v[18:25], v[86:89], v193, v193 op_sel_hi:[0,0,0]
	v_mfma_scale_f32_16x16x128_f8f6f4 v[82:85], v[10:17], v[18:25], v[82:85], v193, v193 op_sel_hi:[0,0,0]
	v_mfma_scale_f32_16x16x128_f8f6f4 v[70:73], v[2:9], v[196:203], v[70:73], v193, v193 op_sel_hi:[0,0,0]
	v_mfma_scale_f32_16x16x128_f8f6f4 v[66:69], v[10:17], v[196:203], v[66:69], v193, v193 op_sel_hi:[0,0,0]
	v_mfma_scale_f32_16x16x128_f8f6f4 v[54:57], v[2:9], v[204:211], v[54:57], v193, v193 op_sel_hi:[0,0,0]
	v_mfma_scale_f32_16x16x128_f8f6f4 v[50:53], v[10:17], v[204:211], v[50:53], v193, v193 op_sel_hi:[0,0,0]
	v_mfma_scale_f32_16x16x128_f8f6f4 v[38:41], v[2:9], v[212:219], v[38:41], v193, v193 op_sel_hi:[0,0,0]
	v_mfma_scale_f32_16x16x128_f8f6f4 v[34:37], v[10:17], v[212:219], v[34:37], v193, v193 op_sel_hi:[0,0,0]
	s_setprio 0
	s_barrier
	s_add_u32 s64, s70, 0x20080
	s_addc_u32 s65, s71, 0
	s_add_i32 s43, s72, s84
	v_lshl_add_u64 v[2:3], s[64:65], 0, v[156:157]
	s_mov_b32 m0, s43
	s_nop 0
	global_load_lds_dwordx4 v[2:3], off
	v_lshl_add_u64 v[2:3], s[64:65], 0, v[160:161]
	s_add_i32 m0, s43, 0x2000
	s_nop 0
	global_load_lds_dwordx4 v[2:3], off
	s_waitcnt vmcnt(6)
	s_barrier
	s_setprio 1
	v_mfma_scale_f32_16x16x128_f8f6f4 v[78:81], v[220:227], v[18:25], v[78:81], v193, v193 op_sel_hi:[0,0,0]
	v_mfma_scale_f32_16x16x128_f8f6f4 v[74:77], v[228:235], v[18:25], v[74:77], v193, v193 op_sel_hi:[0,0,0]
	v_mfma_scale_f32_16x16x128_f8f6f4 v[62:65], v[220:227], v[196:203], v[62:65], v193, v193 op_sel_hi:[0,0,0]
	v_mfma_scale_f32_16x16x128_f8f6f4 v[58:61], v[228:235], v[196:203], v[58:61], v193, v193 op_sel_hi:[0,0,0]
	v_mfma_scale_f32_16x16x128_f8f6f4 v[46:49], v[220:227], v[204:211], v[46:49], v193, v193 op_sel_hi:[0,0,0]
	v_mfma_scale_f32_16x16x128_f8f6f4 v[42:45], v[228:235], v[204:211], v[42:45], v193, v193 op_sel_hi:[0,0,0]
	v_mfma_scale_f32_16x16x128_f8f6f4 v[30:33], v[220:227], v[212:219], v[30:33], v193, v193 op_sel_hi:[0,0,0]
	v_mfma_scale_f32_16x16x128_f8f6f4 v[26:29], v[228:235], v[212:219], v[26:29], v193, v193 op_sel_hi:[0,0,0]
	s_setprio 0
	s_add_i32 s80, s80, 2
	s_add_u32 s68, s68, 0x100
	s_addc_u32 s69, s69, 0
	s_add_u32 vcc_hi, vcc_hi, 0x100
	s_addc_u32 s33, s33, 0
	s_cmp_gt_u32 s80, 5
	s_barrier
	s_cbranch_scc0 .LBB0_330
	s_and_b64 vcc, exec, s[38:39]
	s_cbranch_vccz .LBB0_333
	s_barrier

; __device__ __forceinline__ void ssm_scan(Frame& F, int g, int pm) {
;     const int tid = F.tid, bt = tid >> 7, d = (tid >> 6) & 1, p = tid & 63;
;     const float* apl = (const float*)(F.ws + WS_APL) + ((g * 2 + d) * 64 + p) * 2; const float ar = apl[0], ai = apl[1];
;     const float* ST = (const float*)(F.ws + WS_ST) + ((size_t)(g * 1024 + pm * 256 + bt * NCH)) * 256 + d * 128 + p;
;     bf16* AS = (bf16*)(F.ws + WS_AS) + ((size_t)(g * 1024 + pm * 256 + bt * NCH)) * KTO + 512 + d * 128 + p;
;     float xr = 0.f, xi = 0.f;
;     for (int k0 = 0; k0 < NCH; k0 += 32) {
;         float sr[32], si[32];
; #pragma unroll
;         for (int q = 0; q < 32; ++q) { const int k = d == 0 ? k0 + q : NCH - 1 - (k0 + q); sr[q] = ST[(size_t)k * 256]; si[q] = ST[(size_t)k * 256 + 64]; }
.LBB0_447:
	v_bfe_u32 v1, v0, 6, 1
	s_lshl_b32 s0, s0, 7
	v_lshlrev_b32_e32 v2, 6, v1
	v_or3_b32 v2, v2, s0, v164
	v_lshlrev_b32_e32 v130, 1, v2
	v_lshl_add_u64 v[2:3], v[130:131], 2, s[30:31]
	v_add_co_u32_e32 v2, vcc, 0xf00000, v2
	s_barrier
	s_nop 0
	v_addc_co_u32_e32 v3, vcc, 0, v3, vcc
	s_waitcnt vmcnt(0)
	s_waitcnt vmcnt(0) lgkmcnt(0)
	s_barrier
	v_readfirstlane_b32 s22, v0
	s_nop 3
	s_lshr_b32 s22, s22, 6
	s_cmp_gt_u32 s22, 3
	s_cbranch_scc1 .Lscan_done
	s_and_b32 s23, s22, 1
	s_lshr_b32 s24, s22, 1
	s_cmp_eq_u32 s23, 0
	s_cselect_b32 s25, 1, -1
	s_cselect_b32 s16, 0, 0xfc00
	s_cselect_b32 s18, 0, 0x17a00
	s_lshl_b32 s26, s25, 10
	s_ashr_i32 s27, s26, 31
	s_mul_i32 s36, s25, 0x600
	s_ashr_i32 s37, s36, 31
	v_lshrrev_b32_e32 v1, 5, v164
	v_and_b32_e32 v2, 31, v164
	v_lshl_add_u32 v1, s24, 1, v1
	s_lshl_b32 s38, s23, 6
	s_add_i32 s38, s38, s0
	v_lshl_add_u32 v130, v2, 1, s38
	v_lshl_add_u64 v[12:13], v[130:131], 3, s[30:31]
	v_add_co_u32_e32 v12, vcc, 0xf00000, v12
	s_nop 1
	v_addc_co_u32_e32 v13, vcc, 0, v13, vcc
	global_load_dwordx4 v[12:15], v[12:13], off
	v_lshl_add_u32 v3, v1, 6, s8
	v_lshlrev_b32_e32 v130, 10, v3
	s_lshl_b32 s39, s23, 9
	s_add_i32 s39, s39, s16
	v_add_u32_e32 v130, s39, v130
	v_lshl_add_u32 v130, v2, 3, v130
	v_lshl_add_u64 v[4:5], v[130:131], 0, s[4:5]
	v_mul_u32_u24_e32 v130, 0x600, v3
	s_lshl_b32 s39, s23, 8
	s_add_i32 s39, s39, s18
	v_add_u32_e32 v130, s39, v130
	v_lshl_add_u32 v130, v2, 2, v130
	v_lshl_add_u64 v[6:7], v[130:131], 0, s[30:31]
	v_add_co_u32_e32 v6, vcc, 0xe000400, v6
	s_nop 1
	v_addc_co_u32_e32 v7, vcc, 0, v7, vcc
	v_mov_b32_e32 v8, 0
	v_mov_b32_e32 v9, 0
	v_mov_b32_e32 v10, 0
	v_mov_b32_e32 v11, 0
	global_load_dwordx2 v[16:17], v[4:5], off
	global_load_dwordx2 v[18:19], v[4:5], off offset:256
	v_lshl_add_u64 v[4:5], v[4:5], 0, s[26:27]
	global_load_dwordx2 v[20:21], v[4:5], off
	global_load_dwordx2 v[22:23], v[4:5], off offset:256
	v_lshl_add_u64 v[4:5], v[4:5], 0, s[26:27]
	global_load_dwordx2 v[24:25], v[4:5], off
	global_load_dwordx2 v[26:27], v[4:5], off offset:256
	v_lshl_add_u64 v[4:5], v[4:5], 0, s[26:27]
	global_load_dwordx2 v[28:29], v[4:5], off
	global_load_dwordx2 v[30:31], v[4:5], off offset:256
	v_lshl_add_u64 v[4:5], v[4:5], 0, s[26:27]
	global_load_dwordx2 v[32:33], v[4:5], off
	global_load_dwordx2 v[34:35], v[4:5], off offset:256
	v_lshl_add_u64 v[4:5], v[4:5], 0, s[26:27]
	global_load_dwordx2 v[36:37], v[4:5], off
	global_load_dwordx2 v[38:39], v[4:5], off offset:256
	v_lshl_add_u64 v[4:5], v[4:5], 0, s[26:27]
	global_load_dwordx2 v[40:41], v[4:5], off
	global_load_dwordx2 v[42:43], v[4:5], off offset:256
	v_lshl_add_u64 v[4:5], v[4:5], 0, s[26:27]
	global_load_dwordx2 v[44:45], v[4:5], off
	global_load_dwordx2 v[46:47], v[4:5], off offset:256
	v_lshl_add_u64 v[4:5], v[4:5], 0, s[26:27]
	global_load_dwordx2 v[48:49], v[4:5], off
	global_load_dwordx2 v[50:51], v[4:5], off offset:256
	v_lshl_add_u64 v[4:5], v[4:5], 0, s[26:27]
	global_load_dwordx2 v[52:53], v[4:5], off
	global_load_dwordx2 v[54:55], v[4:5], off offset:256
	v_lshl_add_u64 v[4:5], v[4:5], 0, s[26:27]
	global_load_dwordx2 v[56:57], v[4:5], off
	global_load_dwordx2 v[58:59], v[4:5], off offset:256
	v_lshl_add_u64 v[4:5], v[4:5], 0, s[26:27]
	global_load_dwordx2 v[60:61], v[4:5], off
	global_load_dwordx2 v[62:63], v[4:5], off offset:256
	v_lshl_add_u64 v[4:5], v[4:5], 0, s[26:27]
	global_load_dwordx2 v[64:65], v[4:5], off
	global_load_dwordx2 v[66:67], v[4:5], off offset:256
	v_lshl_add_u64 v[4:5], v[4:5], 0, s[26:27]
	global_load_dwordx2 v[68:69], v[4:5], off
	global_load_dwordx2 v[70:71], v[4:5], off offset:256
	v_lshl_add_u64 v[4:5], v[4:5], 0, s[26:27]
	global_load_dwordx2 v[72:73], v[4:5], off
	global_load_dwordx2 v[74:75], v[4:5], off offset:256
	v_lshl_add_u64 v[4:5], v[4:5], 0, s[26:27]
	global_load_dwordx2 v[76:77], v[4:5], off
	global_load_dwordx2 v[78:79], v[4:5], off offset:256
	v_lshl_add_u64 v[4:5], v[4:5], 0, s[26:27]
	global_load_dwordx2 v[80:81], v[4:5], off
	global_load_dwordx2 v[82:83], v[4:5], off offset:256
	v_lshl_add_u64 v[4:5], v[4:5], 0, s[26:27]
	global_load_dwordx2 v[84:85], v[4:5], off
	global_load_dwordx2 v[86:87], v[4:5], off offset:256
	v_lshl_add_u64 v[4:5], v[4:5], 0, s[26:27]
	global_load_dwordx2 v[88:89], v[4:5], off
	global_load_dwordx2 v[90:91], v[4:5], off offset:256
	v_lshl_add_u64 v[4:5], v[4:5], 0, s[26:27]
	global_load_dwordx2 v[92:93], v[4:5], off
	global_load_dwordx2 v[94:95], v[4:5], off offset:256
	v_lshl_add_u64 v[4:5], v[4:5], 0, s[26:27]
	global_load_dwordx2 v[96:97], v[4:5], off
	global_load_dwordx2 v[98:99], v[4:5], off offset:256
	v_lshl_add_u64 v[4:5], v[4:5], 0, s[26:27]
	global_load_dwordx2 v[100:101], v[4:5], off
	global_load_dwordx2 v[102:103], v[4:5], off offset:256
	v_lshl_add_u64 v[4:5], v[4:5], 0, s[26:27]
	global_load_dwordx2 v[104:105], v[4:5], off
	global_load_dwordx2 v[106:107], v[4:5], off offset:256
	v_lshl_add_u64 v[4:5], v[4:5], 0, s[26:27]
	global_load_dwordx2 v[108:109], v[4:5], off
	global_load_dwordx2 v[110:111], v[4:5], off offset:256
	v_lshl_add_u64 v[4:5], v[4:5], 0, s[26:27]
	global_load_dwordx2 v[112:113], v[4:5], off
	global_load_dwordx2 v[114:115], v[4:5], off offset:256
	v_lshl_add_u64 v[4:5], v[4:5], 0, s[26:27]
	global_load_dwordx2 v[116:117], v[4:5], off
	global_load_dwordx2 v[118:119], v[4:5], off offset:256
	v_lshl_add_u64 v[4:5], v[4:5], 0, s[26:27]
	global_load_dwordx2 v[120:121], v[4:5], off
	global_load_dwordx2 v[122:123], v[4:5], off offset:256
	v_lshl_add_u64 v[4:5], v[4:5], 0, s[26:27]
	global_load_dwordx2 v[124:125], v[4:5], off
	global_load_dwordx2 v[126:127], v[4:5], off offset:256
	v_lshl_add_u64 v[4:5], v[4:5], 0, s[26:27]
	global_load_dwordx2 v[132:133], v[4:5], off
	global_load_dwordx2 v[134:135], v[4:5], off offset:256
	v_lshl_add_u64 v[4:5], v[4:5], 0, s[26:27]
	global_load_dwordx2 v[136:137], v[4:5], off
	global_load_dwordx2 v[138:139], v[4:5], off offset:256
	v_lshl_add_u64 v[4:5], v[4:5], 0, s[26:27]
	global_load_dwordx2 v[140:141], v[4:5], off
	global_load_dwordx2 v[142:143], v[4:5], off offset:256
	v_lshl_add_u64 v[4:5], v[4:5], 0, s[26:27]
	global_load_dwordx2 v[144:145], v[4:5], off
	global_load_dwordx2 v[146:147], v[4:5], off offset:256
	v_lshl_add_u64 v[4:5], v[4:5], 0, s[26:27]
	s_waitcnt vmcnt(62)
; __device__ __forceinline__ unsigned f2bf(float f) { unsigned u = __builtin_bit_cast(unsigned, f); return (u + 0x7fffu + ((u >> 16) & 1u)) >> 16; }
; __device__ __forceinline__ void ssm_scan(Frame& F, int g, int pm) {
;     ...
;     for (int k0 = 0; k0 < NCH; k0 += 32) {
;         float sr[32], si[32];
; #pragma unroll
;         for (int q = 0; q < 32; ++q) { const int k = d == 0 ? k0 + q : NCH - 1 - (k0 + q); sr[q] = ST[(size_t)k * 256]; si[q] = ST[(size_t)k * 256 + 64]; }
; #pragma unroll
;         for (int q = 0; q < 32; ++q) { const int k = d == 0 ? k0 + q : NCH - 1 - (k0 + q);
;             AS[(size_t)k * KTO] = (bf16)f2bf(xr); AS[(size_t)k * KTO + 64] = (bf16)f2bf(xi);
;             const float nr = ar * xr - ai * xi + sr[q], ni = ar * xi + ai * xr + si[q]; xr = nr; xi = ni; }
	v_cvt_pk_bf16_f32 v148, v8, v10
	v_cvt_pk_bf16_f32 v1, v9, v11
	v_mul_f32_e32 v2, v13, v9
	v_mul_f32_e32 v3, v12, v9
	global_store_dword v[6:7], v148, off
	global_store_dword v[6:7], v1, off offset:128
	v_fma_f32 v2, v12, v8, -v2
	v_fma_f32 v3, v13, v8, v3
	v_add_f32_e32 v8, v16, v2
	v_add_f32_e32 v9, v18, v3
	v_mul_f32_e32 v2, v15, v11
	v_mul_f32_e32 v3, v14, v11
	v_fma_f32 v2, v14, v10, -v2
	v_fma_f32 v3, v15, v10, v3
	v_add_f32_e32 v10, v17, v2
	v_add_f32_e32 v11, v19, v3
	v_lshl_add_u64 v[6:7], v[6:7], 0, s[36:37]
	global_load_dwordx2 v[16:17], v[4:5], off
	global_load_dwordx2 v[18:19], v[4:5], off offset:256
	v_lshl_add_u64 v[4:5], v[4:5], 0, s[26:27]
	s_waitcnt vmcnt(62)
	v_cvt_pk_bf16_f32 v148, v8, v10
	v_cvt_pk_bf16_f32 v1, v9, v11
	v_mul_f32_e32 v2, v13, v9
	v_mul_f32_e32 v3, v12, v9
	global_store_dword v[6:7], v148, off
	global_store_dword v[6:7], v1, off offset:128
	v_fma_f32 v2, v12, v8, -v2
	v_fma_f32 v3, v13, v8, v3
	v_add_f32_e32 v8, v20, v2
	v_add_f32_e32 v9, v22, v3
	v_mul_f32_e32 v2, v15, v11
	v_mul_f32_e32 v3, v14, v11
	v_fma_f32 v2, v14, v10, -v2
	v_fma_f32 v3, v15, v10, v3
	v_add_f32_e32 v10, v21, v2
	v_add_f32_e32 v11, v23, v3
	v_lshl_add_u64 v[6:7], v[6:7], 0, s[36:37]
	global_load_dwordx2 v[20:21], v[4:5], off
	global_load_dwordx2 v[22:23], v[4:5], off offset:256
	v_lshl_add_u64 v[4:5], v[4:5], 0, s[26:27]
	s_waitcnt vmcnt(62)
	v_cvt_pk_bf16_f32 v148, v8, v10
	v_cvt_pk_bf16_f32 v1, v9, v11
	v_mul_f32_e32 v2, v13, v9
	v_mul_f32_e32 v3, v12, v9
	global_store_dword v[6:7], v148, off
	global_store_dword v[6:7], v1, off offset:128
	v_fma_f32 v2, v12, v8, -v2
	v_fma_f32 v3, v13, v8, v3
	v_add_f32_e32 v8, v24, v2
	v_add_f32_e32 v9, v26, v3
	v_mul_f32_e32 v2, v15, v11
	v_mul_f32_e32 v3, v14, v11
	v_fma_f32 v2, v14, v10, -v2
	v_fma_f32 v3, v15, v10, v3
	v_add_f32_e32 v10, v25, v2
	v_add_f32_e32 v11, v27, v3
	v_lshl_add_u64 v[6:7], v[6:7], 0, s[36:37]
	global_load_dwordx2 v[24:25], v[4:5], off
	global_load_dwordx2 v[26:27], v[4:5], off offset:256
	v_lshl_add_u64 v[4:5], v[4:5], 0, s[26:27]
	s_waitcnt vmcnt(62)
	v_cvt_pk_bf16_f32 v148, v8, v10
	v_cvt_pk_bf16_f32 v1, v9, v11
	v_mul_f32_e32 v2, v13, v9
	v_mul_f32_e32 v3, v12, v9
	global_store_dword v[6:7], v148, off
	global_store_dword v[6:7], v1, off offset:128
	v_fma_f32 v2, v12, v8, -v2
	v_fma_f32 v3, v13, v8, v3
	v_add_f32_e32 v8, v28, v2
	v_add_f32_e32 v9, v30, v3
	v_mul_f32_e32 v2, v15, v11
	v_mul_f32_e32 v3, v14, v11
	v_fma_f32 v2, v14, v10, -v2
	v_fma_f32 v3, v15, v10, v3
	v_add_f32_e32 v10, v29, v2
	v_add_f32_e32 v11, v31, v3
	v_lshl_add_u64 v[6:7], v[6:7], 0, s[36:37]
	global_load_dwordx2 v[28:29], v[4:5], off
	global_load_dwordx2 v[30:31], v[4:5], off offset:256
	v_lshl_add_u64 v[4:5], v[4:5], 0, s[26:27]
	s_waitcnt vmcnt(62)
	v_cvt_pk_bf16_f32 v148, v8, v10
	v_cvt_pk_bf16_f32 v1, v9, v11
	v_mul_f32_e32 v2, v13, v9
	v_mul_f32_e32 v3, v12, v9
	global_store_dword v[6:7], v148, off
	global_store_dword v[6:7], v1, off offset:128
	v_fma_f32 v2, v12, v8, -v2
	v_fma_f32 v3, v13, v8, v3
	v_add_f32_e32 v8, v32, v2
	v_add_f32_e32 v9, v34, v3
	v_mul_f32_e32 v2, v15, v11
	v_mul_f32_e32 v3, v14, v11
	v_fma_f32 v2, v14, v10, -v2
	v_fma_f32 v3, v15, v10, v3
	v_add_f32_e32 v10, v33, v2
	v_add_f32_e32 v11, v35, v3
	v_lshl_add_u64 v[6:7], v[6:7], 0, s[36:37]
	global_load_dwordx2 v[32:33], v[4:5], off
	global_load_dwordx2 v[34:35], v[4:5], off offset:256
	v_lshl_add_u64 v[4:5], v[4:5], 0, s[26:27]
	s_waitcnt vmcnt(62)
	v_cvt_pk_bf16_f32 v148, v8, v10
	v_cvt_pk_bf16_f32 v1, v9, v11
	v_mul_f32_e32 v2, v13, v9
	v_mul_f32_e32 v3, v12, v9
	global_store_dword v[6:7], v148, off
	global_store_dword v[6:7], v1, off offset:128
	v_fma_f32 v2, v12, v8, -v2
	v_fma_f32 v3, v13, v8, v3
	v_add_f32_e32 v8, v36, v2
	v_add_f32_e32 v9, v38, v3
	v_mul_f32_e32 v2, v15, v11
	v_mul_f32_e32 v3, v14, v11
	v_fma_f32 v2, v14, v10, -v2
	v_fma_f32 v3, v15, v10, v3
	v_add_f32_e32 v10, v37, v2
	v_add_f32_e32 v11, v39, v3
	v_lshl_add_u64 v[6:7], v[6:7], 0, s[36:37]
	global_load_dwordx2 v[36:37], v[4:5], off
	global_load_dwordx2 v[38:39], v[4:5], off offset:256
	v_lshl_add_u64 v[4:5], v[4:5], 0, s[26:27]
	s_waitcnt vmcnt(62)
	v_cvt_pk_bf16_f32 v148, v8, v10
	v_cvt_pk_bf16_f32 v1, v9, v11
	v_mul_f32_e32 v2, v13, v9
	v_mul_f32_e32 v3, v12, v9
	global_store_dword v[6:7], v148, off
	global_store_dword v[6:7], v1, off offset:128
	v_fma_f32 v2, v12, v8, -v2
	v_fma_f32 v3, v13, v8, v3
	v_add_f32_e32 v8, v40, v2
	v_add_f32_e32 v9, v42, v3
	v_mul_f32_e32 v2, v15, v11
	v_mul_f32_e32 v3, v14, v11
	v_fma_f32 v2, v14, v10, -v2
	v_fma_f32 v3, v15, v10, v3
	v_add_f32_e32 v10, v41, v2
	v_add_f32_e32 v11, v43, v3
	v_lshl_add_u64 v[6:7], v[6:7], 0, s[36:37]
	global_load_dwordx2 v[40:41], v[4:5], off
	global_load_dwordx2 v[42:43], v[4:5], off offset:256
	v_lshl_add_u64 v[4:5], v[4:5], 0, s[26:27]
	s_waitcnt vmcnt(62)
	v_cvt_pk_bf16_f32 v148, v8, v10
	v_cvt_pk_bf16_f32 v1, v9, v11
	v_mul_f32_e32 v2, v13, v9
	v_mul_f32_e32 v3, v12, v9
	global_store_dword v[6:7], v148, off
	global_store_dword v[6:7], v1, off offset:128
	v_fma_f32 v2, v12, v8, -v2
	v_fma_f32 v3, v13, v8, v3
	v_add_f32_e32 v8, v44, v2
	v_add_f32_e32 v9, v46, v3
	v_mul_f32_e32 v2, v15, v11
	v_mul_f32_e32 v3, v14, v11
	v_fma_f32 v2, v14, v10, -v2
	v_fma_f32 v3, v15, v10, v3
	v_add_f32_e32 v10, v45, v2
	v_add_f32_e32 v11, v47, v3
	v_lshl_add_u64 v[6:7], v[6:7], 0, s[36:37]
	global_load_dwordx2 v[44:45], v[4:5], off
	global_load_dwordx2 v[46:47], v[4:5], off offset:256
	v_lshl_add_u64 v[4:5], v[4:5], 0, s[26:27]
	s_waitcnt vmcnt(62)
; __device__ __forceinline__ unsigned f2bf(float f) { unsigned u = __builtin_bit_cast(unsigned, f); return (u + 0x7fffu + ((u >> 16) & 1u)) >> 16; }
; __device__ __forceinline__ void ssm_scan(Frame& F, int g, int pm) {
;     ...
;     for (int k0 = 0; k0 < NCH; k0 += 32) {
;         float sr[32], si[32];
; #pragma unroll
;         for (int q = 0; q < 32; ++q) { const int k = d == 0 ? k0 + q : NCH - 1 - (k0 + q); sr[q] = ST[(size_t)k * 256]; si[q] = ST[(size_t)k * 256 + 64]; }
; #pragma unroll
;         for (int q = 0; q < 32; ++q) { const int k = d == 0 ? k0 + q : NCH - 1 - (k0 + q);
;             AS[(size_t)k * KTO] = (bf16)f2bf(xr); AS[(size_t)k * KTO + 64] = (bf16)f2bf(xi);
;             const float nr = ar * xr - ai * xi + sr[q], ni = ar * xi + ai * xr + si[q]; xr = nr; xi = ni; }
	v_cvt_pk_bf16_f32 v148, v8, v10
	v_cvt_pk_bf16_f32 v1, v9, v11
	v_mul_f32_e32 v2, v13, v9
	v_mul_f32_e32 v3, v12, v9
	global_store_dword v[6:7], v148, off
	global_store_dword v[6:7], v1, off offset:128
	v_fma_f32 v2, v12, v8, -v2
	v_fma_f32 v3, v13, v8, v3
	v_add_f32_e32 v8, v48, v2
	v_add_f32_e32 v9, v50, v3
	v_mul_f32_e32 v2, v15, v11
	v_mul_f32_e32 v3, v14, v11
	v_fma_f32 v2, v14, v10, -v2
	v_fma_f32 v3, v15, v10, v3
	v_add_f32_e32 v10, v49, v2
	v_add_f32_e32 v11, v51, v3
	v_lshl_add_u64 v[6:7], v[6:7], 0, s[36:37]
	global_load_dwordx2 v[48:49], v[4:5], off
	global_load_dwordx2 v[50:51], v[4:5], off offset:256
	v_lshl_add_u64 v[4:5], v[4:5], 0, s[26:27]
	s_waitcnt vmcnt(62)
	v_cvt_pk_bf16_f32 v148, v8, v10
	v_cvt_pk_bf16_f32 v1, v9, v11
	v_mul_f32_e32 v2, v13, v9
	v_mul_f32_e32 v3, v12, v9
	global_store_dword v[6:7], v148, off
	global_store_dword v[6:7], v1, off offset:128
	v_fma_f32 v2, v12, v8, -v2
	v_fma_f32 v3, v13, v8, v3
	v_add_f32_e32 v8, v52, v2
	v_add_f32_e32 v9, v54, v3
	v_mul_f32_e32 v2, v15, v11
	v_mul_f32_e32 v3, v14, v11
	v_fma_f32 v2, v14, v10, -v2
	v_fma_f32 v3, v15, v10, v3
	v_add_f32_e32 v10, v53, v2
	v_add_f32_e32 v11, v55, v3
	v_lshl_add_u64 v[6:7], v[6:7], 0, s[36:37]
	global_load_dwordx2 v[52:53], v[4:5], off
	global_load_dwordx2 v[54:55], v[4:5], off offset:256
	v_lshl_add_u64 v[4:5], v[4:5], 0, s[26:27]
	s_waitcnt vmcnt(62)
	v_cvt_pk_bf16_f32 v148, v8, v10
	v_cvt_pk_bf16_f32 v1, v9, v11
	v_mul_f32_e32 v2, v13, v9
	v_mul_f32_e32 v3, v12, v9
	global_store_dword v[6:7], v148, off
	global_store_dword v[6:7], v1, off offset:128
	v_fma_f32 v2, v12, v8, -v2
	v_fma_f32 v3, v13, v8, v3
	v_add_f32_e32 v8, v56, v2
	v_add_f32_e32 v9, v58, v3
	v_mul_f32_e32 v2, v15, v11
	v_mul_f32_e32 v3, v14, v11
	v_fma_f32 v2, v14, v10, -v2
	v_fma_f32 v3, v15, v10, v3
	v_add_f32_e32 v10, v57, v2
	v_add_f32_e32 v11, v59, v3
	v_lshl_add_u64 v[6:7], v[6:7], 0, s[36:37]
	global_load_dwordx2 v[56:57], v[4:5], off
	global_load_dwordx2 v[58:59], v[4:5], off offset:256
	v_lshl_add_u64 v[4:5], v[4:5], 0, s[26:27]
	s_waitcnt vmcnt(62)
	v_cvt_pk_bf16_f32 v148, v8, v10
	v_cvt_pk_bf16_f32 v1, v9, v11
	v_mul_f32_e32 v2, v13, v9
	v_mul_f32_e32 v3, v12, v9
	global_store_dword v[6:7], v148, off
	global_store_dword v[6:7], v1, off offset:128
	v_fma_f32 v2, v12, v8, -v2
	v_fma_f32 v3, v13, v8, v3
	v_add_f32_e32 v8, v60, v2
	v_add_f32_e32 v9, v62, v3
	v_mul_f32_e32 v2, v15, v11
	v_mul_f32_e32 v3, v14, v11
	v_fma_f32 v2, v14, v10, -v2
	v_fma_f32 v3, v15, v10, v3
	v_add_f32_e32 v10, v61, v2
	v_add_f32_e32 v11, v63, v3
	v_lshl_add_u64 v[6:7], v[6:7], 0, s[36:37]
	global_load_dwordx2 v[60:61], v[4:5], off
	global_load_dwordx2 v[62:63], v[4:5], off offset:256
	v_lshl_add_u64 v[4:5], v[4:5], 0, s[26:27]
	s_waitcnt vmcnt(62)
	v_cvt_pk_bf16_f32 v148, v8, v10
	v_cvt_pk_bf16_f32 v1, v9, v11
	v_mul_f32_e32 v2, v13, v9
	v_mul_f32_e32 v3, v12, v9
	global_store_dword v[6:7], v148, off
	global_store_dword v[6:7], v1, off offset:128
	v_fma_f32 v2, v12, v8, -v2
	v_fma_f32 v3, v13, v8, v3
	v_add_f32_e32 v8, v64, v2
	v_add_f32_e32 v9, v66, v3
	v_mul_f32_e32 v2, v15, v11
	v_mul_f32_e32 v3, v14, v11
	v_fma_f32 v2, v14, v10, -v2
	v_fma_f32 v3, v15, v10, v3
	v_add_f32_e32 v10, v65, v2
	v_add_f32_e32 v11, v67, v3
	v_lshl_add_u64 v[6:7], v[6:7], 0, s[36:37]
	global_load_dwordx2 v[64:65], v[4:5], off
	global_load_dwordx2 v[66:67], v[4:5], off offset:256
	v_lshl_add_u64 v[4:5], v[4:5], 0, s[26:27]
	s_waitcnt vmcnt(62)
	v_cvt_pk_bf16_f32 v148, v8, v10
	v_cvt_pk_bf16_f32 v1, v9, v11
	v_mul_f32_e32 v2, v13, v9
	v_mul_f32_e32 v3, v12, v9
	global_store_dword v[6:7], v148, off
	global_store_dword v[6:7], v1, off offset:128
	v_fma_f32 v2, v12, v8, -v2
	v_fma_f32 v3, v13, v8, v3
	v_add_f32_e32 v8, v68, v2
	v_add_f32_e32 v9, v70, v3
	v_mul_f32_e32 v2, v15, v11
	v_mul_f32_e32 v3, v14, v11
	v_fma_f32 v2, v14, v10, -v2
	v_fma_f32 v3, v15, v10, v3
	v_add_f32_e32 v10, v69, v2
	v_add_f32_e32 v11, v71, v3
	v_lshl_add_u64 v[6:7], v[6:7], 0, s[36:37]
	global_load_dwordx2 v[68:69], v[4:5], off
	global_load_dwordx2 v[70:71], v[4:5], off offset:256
	v_lshl_add_u64 v[4:5], v[4:5], 0, s[26:27]
	s_waitcnt vmcnt(62)
	v_cvt_pk_bf16_f32 v148, v8, v10
	v_cvt_pk_bf16_f32 v1, v9, v11
	v_mul_f32_e32 v2, v13, v9
	v_mul_f32_e32 v3, v12, v9
	global_store_dword v[6:7], v148, off
	global_store_dword v[6:7], v1, off offset:128
	v_fma_f32 v2, v12, v8, -v2
	v_fma_f32 v3, v13, v8, v3
	v_add_f32_e32 v8, v72, v2
	v_add_f32_e32 v9, v74, v3
	v_mul_f32_e32 v2, v15, v11
	v_mul_f32_e32 v3, v14, v11
	v_fma_f32 v2, v14, v10, -v2
	v_fma_f32 v3, v15, v10, v3
	v_add_f32_e32 v10, v73, v2
	v_add_f32_e32 v11, v75, v3
	v_lshl_add_u64 v[6:7], v[6:7], 0, s[36:37]
	global_load_dwordx2 v[72:73], v[4:5], off
	global_load_dwordx2 v[74:75], v[4:5], off offset:256
	v_lshl_add_u64 v[4:5], v[4:5], 0, s[26:27]
	s_waitcnt vmcnt(62)
	v_cvt_pk_bf16_f32 v148, v8, v10
	v_cvt_pk_bf16_f32 v1, v9, v11
	v_mul_f32_e32 v2, v13, v9
	v_mul_f32_e32 v3, v12, v9
	global_store_dword v[6:7], v148, off
	global_store_dword v[6:7], v1, off offset:128
	v_fma_f32 v2, v12, v8, -v2
	v_fma_f32 v3, v13, v8, v3
	v_add_f32_e32 v8, v76, v2
	v_add_f32_e32 v9, v78, v3
	v_mul_f32_e32 v2, v15, v11
	v_mul_f32_e32 v3, v14, v11
	v_fma_f32 v2, v14, v10, -v2
	v_fma_f32 v3, v15, v10, v3
	v_add_f32_e32 v10, v77, v2
	v_add_f32_e32 v11, v79, v3
	v_lshl_add_u64 v[6:7], v[6:7], 0, s[36:37]
	global_load_dwordx2 v[76:77], v[4:5], off
	global_load_dwordx2 v[78:79], v[4:5], off offset:256
	v_lshl_add_u64 v[4:5], v[4:5], 0, s[26:27]
	s_waitcnt vmcnt(62)
; __device__ __forceinline__ unsigned f2bf(float f) { unsigned u = __builtin_bit_cast(unsigned, f); return (u + 0x7fffu + ((u >> 16) & 1u)) >> 16; }
; __device__ __forceinline__ void ssm_scan(Frame& F, int g, int pm) {
;     ...
;     for (int k0 = 0; k0 < NCH; k0 += 32) {
;         float sr[32], si[32];
; #pragma unroll
;         for (int q = 0; q < 32; ++q) { const int k = d == 0 ? k0 + q : NCH - 1 - (k0 + q); sr[q] = ST[(size_t)k * 256]; si[q] = ST[(size_t)k * 256 + 64]; }
; #pragma unroll
;         for (int q = 0; q < 32; ++q) { const int k = d == 0 ? k0 + q : NCH - 1 - (k0 + q);
;             AS[(size_t)k * KTO] = (bf16)f2bf(xr); AS[(size_t)k * KTO + 64] = (bf16)f2bf(xi);
;             const float nr = ar * xr - ai * xi + sr[q], ni = ar * xi + ai * xr + si[q]; xr = nr; xi = ni; }
	v_cvt_pk_bf16_f32 v148, v8, v10
	v_cvt_pk_bf16_f32 v1, v9, v11
	v_mul_f32_e32 v2, v13, v9
	v_mul_f32_e32 v3, v12, v9
	global_store_dword v[6:7], v148, off
	global_store_dword v[6:7], v1, off offset:128
	v_fma_f32 v2, v12, v8, -v2
	v_fma_f32 v3, v13, v8, v3
	v_add_f32_e32 v8, v80, v2
	v_add_f32_e32 v9, v82, v3
	v_mul_f32_e32 v2, v15, v11
	v_mul_f32_e32 v3, v14, v11
	v_fma_f32 v2, v14, v10, -v2
	v_fma_f32 v3, v15, v10, v3
	v_add_f32_e32 v10, v81, v2
	v_add_f32_e32 v11, v83, v3
	v_lshl_add_u64 v[6:7], v[6:7], 0, s[36:37]
	global_load_dwordx2 v[80:81], v[4:5], off
	global_load_dwordx2 v[82:83], v[4:5], off offset:256
	v_lshl_add_u64 v[4:5], v[4:5], 0, s[26:27]
	s_waitcnt vmcnt(62)
	v_cvt_pk_bf16_f32 v148, v8, v10
	v_cvt_pk_bf16_f32 v1, v9, v11
	v_mul_f32_e32 v2, v13, v9
	v_mul_f32_e32 v3, v12, v9
	global_store_dword v[6:7], v148, off
	global_store_dword v[6:7], v1, off offset:128
	v_fma_f32 v2, v12, v8, -v2
	v_fma_f32 v3, v13, v8, v3
	v_add_f32_e32 v8, v84, v2
	v_add_f32_e32 v9, v86, v3
	v_mul_f32_e32 v2, v15, v11
	v_mul_f32_e32 v3, v14, v11
	v_fma_f32 v2, v14, v10, -v2
	v_fma_f32 v3, v15, v10, v3
	v_add_f32_e32 v10, v85, v2
	v_add_f32_e32 v11, v87, v3
	v_lshl_add_u64 v[6:7], v[6:7], 0, s[36:37]
	global_load_dwordx2 v[84:85], v[4:5], off
	global_load_dwordx2 v[86:87], v[4:5], off offset:256
	v_lshl_add_u64 v[4:5], v[4:5], 0, s[26:27]
	s_waitcnt vmcnt(62)
	v_cvt_pk_bf16_f32 v148, v8, v10
	v_cvt_pk_bf16_f32 v1, v9, v11
	v_mul_f32_e32 v2, v13, v9
	v_mul_f32_e32 v3, v12, v9
	global_store_dword v[6:7], v148, off
	global_store_dword v[6:7], v1, off offset:128
	v_fma_f32 v2, v12, v8, -v2
	v_fma_f32 v3, v13, v8, v3
	v_add_f32_e32 v8, v88, v2
	v_add_f32_e32 v9, v90, v3
	v_mul_f32_e32 v2, v15, v11
	v_mul_f32_e32 v3, v14, v11
	v_fma_f32 v2, v14, v10, -v2
	v_fma_f32 v3, v15, v10, v3
	v_add_f32_e32 v10, v89, v2
	v_add_f32_e32 v11, v91, v3
	v_lshl_add_u64 v[6:7], v[6:7], 0, s[36:37]
	global_load_dwordx2 v[88:89], v[4:5], off
	global_load_dwordx2 v[90:91], v[4:5], off offset:256
	v_lshl_add_u64 v[4:5], v[4:5], 0, s[26:27]
	s_waitcnt vmcnt(62)
	v_cvt_pk_bf16_f32 v148, v8, v10
	v_cvt_pk_bf16_f32 v1, v9, v11
	v_mul_f32_e32 v2, v13, v9
	v_mul_f32_e32 v3, v12, v9
	global_store_dword v[6:7], v148, off
	global_store_dword v[6:7], v1, off offset:128
	v_fma_f32 v2, v12, v8, -v2
	v_fma_f32 v3, v13, v8, v3
	v_add_f32_e32 v8, v92, v2
	v_add_f32_e32 v9, v94, v3
	v_mul_f32_e32 v2, v15, v11
	v_mul_f32_e32 v3, v14, v11
	v_fma_f32 v2, v14, v10, -v2
	v_fma_f32 v3, v15, v10, v3
	v_add_f32_e32 v10, v93, v2
	v_add_f32_e32 v11, v95, v3
	v_lshl_add_u64 v[6:7], v[6:7], 0, s[36:37]
	global_load_dwordx2 v[92:93], v[4:5], off
	global_load_dwordx2 v[94:95], v[4:5], off offset:256
	v_lshl_add_u64 v[4:5], v[4:5], 0, s[26:27]
	s_waitcnt vmcnt(62)
	v_cvt_pk_bf16_f32 v148, v8, v10
	v_cvt_pk_bf16_f32 v1, v9, v11
	v_mul_f32_e32 v2, v13, v9
	v_mul_f32_e32 v3, v12, v9
	global_store_dword v[6:7], v148, off
	global_store_dword v[6:7], v1, off offset:128
	v_fma_f32 v2, v12, v8, -v2
	v_fma_f32 v3, v13, v8, v3
	v_add_f32_e32 v8, v96, v2
	v_add_f32_e32 v9, v98, v3
	v_mul_f32_e32 v2, v15, v11
	v_mul_f32_e32 v3, v14, v11
	v_fma_f32 v2, v14, v10, -v2
	v_fma_f32 v3, v15, v10, v3
	v_add_f32_e32 v10, v97, v2
	v_add_f32_e32 v11, v99, v3
	v_lshl_add_u64 v[6:7], v[6:7], 0, s[36:37]
	global_load_dwordx2 v[96:97], v[4:5], off
	global_load_dwordx2 v[98:99], v[4:5], off offset:256
	v_lshl_add_u64 v[4:5], v[4:5], 0, s[26:27]
	s_waitcnt vmcnt(62)
	v_cvt_pk_bf16_f32 v148, v8, v10
	v_cvt_pk_bf16_f32 v1, v9, v11
	v_mul_f32_e32 v2, v13, v9
	v_mul_f32_e32 v3, v12, v9
	global_store_dword v[6:7], v148, off
	global_store_dword v[6:7], v1, off offset:128
	v_fma_f32 v2, v12, v8, -v2
	v_fma_f32 v3, v13, v8, v3
	v_add_f32_e32 v8, v100, v2
	v_add_f32_e32 v9, v102, v3
	v_mul_f32_e32 v2, v15, v11
	v_mul_f32_e32 v3, v14, v11
	v_fma_f32 v2, v14, v10, -v2
	v_fma_f32 v3, v15, v10, v3
	v_add_f32_e32 v10, v101, v2
	v_add_f32_e32 v11, v103, v3
	v_lshl_add_u64 v[6:7], v[6:7], 0, s[36:37]
	global_load_dwordx2 v[100:101], v[4:5], off
	global_load_dwordx2 v[102:103], v[4:5], off offset:256
	v_lshl_add_u64 v[4:5], v[4:5], 0, s[26:27]
	s_waitcnt vmcnt(62)
	v_cvt_pk_bf16_f32 v148, v8, v10
	v_cvt_pk_bf16_f32 v1, v9, v11
	v_mul_f32_e32 v2, v13, v9
	v_mul_f32_e32 v3, v12, v9
	global_store_dword v[6:7], v148, off
	global_store_dword v[6:7], v1, off offset:128
	v_fma_f32 v2, v12, v8, -v2
	v_fma_f32 v3, v13, v8, v3
	v_add_f32_e32 v8, v104, v2
	v_add_f32_e32 v9, v106, v3
	v_mul_f32_e32 v2, v15, v11
	v_mul_f32_e32 v3, v14, v11
	v_fma_f32 v2, v14, v10, -v2
	v_fma_f32 v3, v15, v10, v3
	v_add_f32_e32 v10, v105, v2
	v_add_f32_e32 v11, v107, v3
	v_lshl_add_u64 v[6:7], v[6:7], 0, s[36:37]
	global_load_dwordx2 v[104:105], v[4:5], off
	global_load_dwordx2 v[106:107], v[4:5], off offset:256
	v_lshl_add_u64 v[4:5], v[4:5], 0, s[26:27]
	s_waitcnt vmcnt(62)
	v_cvt_pk_bf16_f32 v148, v8, v10
	v_cvt_pk_bf16_f32 v1, v9, v11
	v_mul_f32_e32 v2, v13, v9
	v_mul_f32_e32 v3, v12, v9
	global_store_dword v[6:7], v148, off
	global_store_dword v[6:7], v1, off offset:128
	v_fma_f32 v2, v12, v8, -v2
	v_fma_f32 v3, v13, v8, v3
	v_add_f32_e32 v8, v108, v2
	v_add_f32_e32 v9, v110, v3
	v_mul_f32_e32 v2, v15, v11
	v_mul_f32_e32 v3, v14, v11
	v_fma_f32 v2, v14, v10, -v2
	v_fma_f32 v3, v15, v10, v3
	v_add_f32_e32 v10, v109, v2
	v_add_f32_e32 v11, v111, v3
	v_lshl_add_u64 v[6:7], v[6:7], 0, s[36:37]
	global_load_dwordx2 v[108:109], v[4:5], off
	global_load_dwordx2 v[110:111], v[4:5], off offset:256
	v_lshl_add_u64 v[4:5], v[4:5], 0, s[26:27]
	s_waitcnt vmcnt(62)
; __device__ __forceinline__ unsigned f2bf(float f) { unsigned u = __builtin_bit_cast(unsigned, f); return (u + 0x7fffu + ((u >> 16) & 1u)) >> 16; }
; __device__ __forceinline__ void ssm_scan(Frame& F, int g, int pm) {
;     ...
;     for (int k0 = 0; k0 < NCH; k0 += 32) {
;         float sr[32], si[32];
; #pragma unroll
;         for (int q = 0; q < 32; ++q) { const int k = d == 0 ? k0 + q : NCH - 1 - (k0 + q); sr[q] = ST[(size_t)k * 256]; si[q] = ST[(size_t)k * 256 + 64]; }
; #pragma unroll
;         for (int q = 0; q < 32; ++q) { const int k = d == 0 ? k0 + q : NCH - 1 - (k0 + q);
;             AS[(size_t)k * KTO] = (bf16)f2bf(xr); AS[(size_t)k * KTO + 64] = (bf16)f2bf(xi);
;             const float nr = ar * xr - ai * xi + sr[q], ni = ar * xi + ai * xr + si[q]; xr = nr; xi = ni; }
	v_cvt_pk_bf16_f32 v148, v8, v10
	v_cvt_pk_bf16_f32 v1, v9, v11
	v_mul_f32_e32 v2, v13, v9
	v_mul_f32_e32 v3, v12, v9
	global_store_dword v[6:7], v148, off
	global_store_dword v[6:7], v1, off offset:128
	v_fma_f32 v2, v12, v8, -v2
	v_fma_f32 v3, v13, v8, v3
	v_add_f32_e32 v8, v112, v2
	v_add_f32_e32 v9, v114, v3
	v_mul_f32_e32 v2, v15, v11
	v_mul_f32_e32 v3, v14, v11
	v_fma_f32 v2, v14, v10, -v2
	v_fma_f32 v3, v15, v10, v3
	v_add_f32_e32 v10, v113, v2
	v_add_f32_e32 v11, v115, v3
	v_lshl_add_u64 v[6:7], v[6:7], 0, s[36:37]
	global_load_dwordx2 v[112:113], v[4:5], off
	global_load_dwordx2 v[114:115], v[4:5], off offset:256
	v_lshl_add_u64 v[4:5], v[4:5], 0, s[26:27]
	s_waitcnt vmcnt(62)
	v_cvt_pk_bf16_f32 v148, v8, v10
	v_cvt_pk_bf16_f32 v1, v9, v11
	v_mul_f32_e32 v2, v13, v9
	v_mul_f32_e32 v3, v12, v9
	global_store_dword v[6:7], v148, off
	global_store_dword v[6:7], v1, off offset:128
	v_fma_f32 v2, v12, v8, -v2
	v_fma_f32 v3, v13, v8, v3
	v_add_f32_e32 v8, v116, v2
	v_add_f32_e32 v9, v118, v3
	v_mul_f32_e32 v2, v15, v11
	v_mul_f32_e32 v3, v14, v11
	v_fma_f32 v2, v14, v10, -v2
	v_fma_f32 v3, v15, v10, v3
	v_add_f32_e32 v10, v117, v2
	v_add_f32_e32 v11, v119, v3
	v_lshl_add_u64 v[6:7], v[6:7], 0, s[36:37]
	global_load_dwordx2 v[116:117], v[4:5], off
	global_load_dwordx2 v[118:119], v[4:5], off offset:256
	v_lshl_add_u64 v[4:5], v[4:5], 0, s[26:27]
	s_waitcnt vmcnt(62)
	v_cvt_pk_bf16_f32 v148, v8, v10
	v_cvt_pk_bf16_f32 v1, v9, v11
	v_mul_f32_e32 v2, v13, v9
	v_mul_f32_e32 v3, v12, v9
	global_store_dword v[6:7], v148, off
	global_store_dword v[6:7], v1, off offset:128
	v_fma_f32 v2, v12, v8, -v2
	v_fma_f32 v3, v13, v8, v3
	v_add_f32_e32 v8, v120, v2
	v_add_f32_e32 v9, v122, v3
	v_mul_f32_e32 v2, v15, v11
	v_mul_f32_e32 v3, v14, v11
	v_fma_f32 v2, v14, v10, -v2
	v_fma_f32 v3, v15, v10, v3
	v_add_f32_e32 v10, v121, v2
	v_add_f32_e32 v11, v123, v3
	v_lshl_add_u64 v[6:7], v[6:7], 0, s[36:37]
	global_load_dwordx2 v[120:121], v[4:5], off
	global_load_dwordx2 v[122:123], v[4:5], off offset:256
	v_lshl_add_u64 v[4:5], v[4:5], 0, s[26:27]
	s_waitcnt vmcnt(62)
	v_cvt_pk_bf16_f32 v148, v8, v10
	v_cvt_pk_bf16_f32 v1, v9, v11
	v_mul_f32_e32 v2, v13, v9
	v_mul_f32_e32 v3, v12, v9
	global_store_dword v[6:7], v148, off
	global_store_dword v[6:7], v1, off offset:128
	v_fma_f32 v2, v12, v8, -v2
	v_fma_f32 v3, v13, v8, v3
	v_add_f32_e32 v8, v124, v2
	v_add_f32_e32 v9, v126, v3
	v_mul_f32_e32 v2, v15, v11
	v_mul_f32_e32 v3, v14, v11
	v_fma_f32 v2, v14, v10, -v2
	v_fma_f32 v3, v15, v10, v3
	v_add_f32_e32 v10, v125, v2
	v_add_f32_e32 v11, v127, v3
	v_lshl_add_u64 v[6:7], v[6:7], 0, s[36:37]
	global_load_dwordx2 v[124:125], v[4:5], off
	global_load_dwordx2 v[126:127], v[4:5], off offset:256
	v_lshl_add_u64 v[4:5], v[4:5], 0, s[26:27]
	s_waitcnt vmcnt(62)
	v_cvt_pk_bf16_f32 v148, v8, v10
	v_cvt_pk_bf16_f32 v1, v9, v11
	v_mul_f32_e32 v2, v13, v9
	v_mul_f32_e32 v3, v12, v9
	global_store_dword v[6:7], v148, off
	global_store_dword v[6:7], v1, off offset:128
	v_fma_f32 v2, v12, v8, -v2
	v_fma_f32 v3, v13, v8, v3
	v_add_f32_e32 v8, v132, v2
	v_add_f32_e32 v9, v134, v3
	v_mul_f32_e32 v2, v15, v11
	v_mul_f32_e32 v3, v14, v11
	v_fma_f32 v2, v14, v10, -v2
	v_fma_f32 v3, v15, v10, v3
	v_add_f32_e32 v10, v133, v2
	v_add_f32_e32 v11, v135, v3
	v_lshl_add_u64 v[6:7], v[6:7], 0, s[36:37]
	global_load_dwordx2 v[132:133], v[4:5], off
	global_load_dwordx2 v[134:135], v[4:5], off offset:256
	v_lshl_add_u64 v[4:5], v[4:5], 0, s[26:27]
	s_waitcnt vmcnt(62)
	v_cvt_pk_bf16_f32 v148, v8, v10
	v_cvt_pk_bf16_f32 v1, v9, v11
	v_mul_f32_e32 v2, v13, v9
	v_mul_f32_e32 v3, v12, v9
	global_store_dword v[6:7], v148, off
	global_store_dword v[6:7], v1, off offset:128
	v_fma_f32 v2, v12, v8, -v2
	v_fma_f32 v3, v13, v8, v3
	v_add_f32_e32 v8, v136, v2
	v_add_f32_e32 v9, v138, v3
	v_mul_f32_e32 v2, v15, v11
	v_mul_f32_e32 v3, v14, v11
	v_fma_f32 v2, v14, v10, -v2
	v_fma_f32 v3, v15, v10, v3
	v_add_f32_e32 v10, v137, v2
	v_add_f32_e32 v11, v139, v3
	v_lshl_add_u64 v[6:7], v[6:7], 0, s[36:37]
	global_load_dwordx2 v[136:137], v[4:5], off
	global_load_dwordx2 v[138:139], v[4:5], off offset:256
	v_lshl_add_u64 v[4:5], v[4:5], 0, s[26:27]
	s_waitcnt vmcnt(62)
	v_cvt_pk_bf16_f32 v148, v8, v10
	v_cvt_pk_bf16_f32 v1, v9, v11
	v_mul_f32_e32 v2, v13, v9
	v_mul_f32_e32 v3, v12, v9
	global_store_dword v[6:7], v148, off
	global_store_dword v[6:7], v1, off offset:128
	v_fma_f32 v2, v12, v8, -v2
	v_fma_f32 v3, v13, v8, v3
	v_add_f32_e32 v8, v140, v2
	v_add_f32_e32 v9, v142, v3
	v_mul_f32_e32 v2, v15, v11
	v_mul_f32_e32 v3, v14, v11
	v_fma_f32 v2, v14, v10, -v2
	v_fma_f32 v3, v15, v10, v3
	v_add_f32_e32 v10, v141, v2
	v_add_f32_e32 v11, v143, v3
	v_lshl_add_u64 v[6:7], v[6:7], 0, s[36:37]
	global_load_dwordx2 v[140:141], v[4:5], off
	global_load_dwordx2 v[142:143], v[4:5], off offset:256
	v_lshl_add_u64 v[4:5], v[4:5], 0, s[26:27]
	s_waitcnt vmcnt(62)
	v_cvt_pk_bf16_f32 v148, v8, v10
	v_cvt_pk_bf16_f32 v1, v9, v11
	v_mul_f32_e32 v2, v13, v9
	v_mul_f32_e32 v3, v12, v9
	global_store_dword v[6:7], v148, off
	global_store_dword v[6:7], v1, off offset:128
	v_fma_f32 v2, v12, v8, -v2
	v_fma_f32 v3, v13, v8, v3
	v_add_f32_e32 v8, v144, v2
	v_add_f32_e32 v9, v146, v3
	v_mul_f32_e32 v2, v15, v11
	v_mul_f32_e32 v3, v14, v11
	v_fma_f32 v2, v14, v10, -v2
	v_fma_f32 v3, v15, v10, v3
	v_add_f32_e32 v10, v145, v2
	v_add_f32_e32 v11, v147, v3
	v_lshl_add_u64 v[6:7], v[6:7], 0, s[36:37]
	global_load_dwordx2 v[144:145], v[4:5], off
	global_load_dwordx2 v[146:147], v[4:5], off offset:256
	s_waitcnt vmcnt(60)
; __device__ __forceinline__ unsigned f2bf(float f) { unsigned u = __builtin_bit_cast(unsigned, f); return (u + 0x7fffu + ((u >> 16) & 1u)) >> 16; }
; __device__ __forceinline__ void ssm_scan(Frame& F, int g, int pm) {
;     ...
;     for (int k0 = 0; k0 < NCH; k0 += 32) {
;         float sr[32], si[32];
; #pragma unroll
;         for (int q = 0; q < 32; ++q) { const int k = d == 0 ? k0 + q : NCH - 1 - (k0 + q); sr[q] = ST[(size_t)k * 256]; si[q] = ST[(size_t)k * 256 + 64]; }
; #pragma unroll
;         for (int q = 0; q < 32; ++q) { const int k = d == 0 ? k0 + q : NCH - 1 - (k0 + q);
;             AS[(size_t)k * KTO] = (bf16)f2bf(xr); AS[(size_t)k * KTO + 64] = (bf16)f2bf(xi);
;             const float nr = ar * xr - ai * xi + sr[q], ni = ar * xi + ai * xr + si[q]; xr = nr; xi = ni; }
	v_cvt_pk_bf16_f32 v148, v8, v10
	v_cvt_pk_bf16_f32 v1, v9, v11
	v_mul_f32_e32 v2, v13, v9
	v_mul_f32_e32 v3, v12, v9
	global_store_dword v[6:7], v148, off
	global_store_dword v[6:7], v1, off offset:128
	v_fma_f32 v2, v12, v8, -v2
	v_fma_f32 v3, v13, v8, v3
	v_add_f32_e32 v8, v16, v2
	v_add_f32_e32 v9, v18, v3
	v_mul_f32_e32 v2, v15, v11
	v_mul_f32_e32 v3, v14, v11
	v_fma_f32 v2, v14, v10, -v2
	v_fma_f32 v3, v15, v10, v3
	v_add_f32_e32 v10, v17, v2
	v_add_f32_e32 v11, v19, v3
	v_lshl_add_u64 v[6:7], v[6:7], 0, s[36:37]
	s_waitcnt vmcnt(60)
	v_cvt_pk_bf16_f32 v148, v8, v10
	v_cvt_pk_bf16_f32 v1, v9, v11
	v_mul_f32_e32 v2, v13, v9
	v_mul_f32_e32 v3, v12, v9
	global_store_dword v[6:7], v148, off
	global_store_dword v[6:7], v1, off offset:128
	v_fma_f32 v2, v12, v8, -v2
	v_fma_f32 v3, v13, v8, v3
	v_add_f32_e32 v8, v20, v2
	v_add_f32_e32 v9, v22, v3
	v_mul_f32_e32 v2, v15, v11
	v_mul_f32_e32 v3, v14, v11
	v_fma_f32 v2, v14, v10, -v2
	v_fma_f32 v3, v15, v10, v3
	v_add_f32_e32 v10, v21, v2
	v_add_f32_e32 v11, v23, v3
	v_lshl_add_u64 v[6:7], v[6:7], 0, s[36:37]
	s_waitcnt vmcnt(60)
	v_cvt_pk_bf16_f32 v148, v8, v10
	v_cvt_pk_bf16_f32 v1, v9, v11
	v_mul_f32_e32 v2, v13, v9
	v_mul_f32_e32 v3, v12, v9
	global_store_dword v[6:7], v148, off
	global_store_dword v[6:7], v1, off offset:128
	v_fma_f32 v2, v12, v8, -v2
	v_fma_f32 v3, v13, v8, v3
	v_add_f32_e32 v8, v24, v2
	v_add_f32_e32 v9, v26, v3
	v_mul_f32_e32 v2, v15, v11
	v_mul_f32_e32 v3, v14, v11
	v_fma_f32 v2, v14, v10, -v2
	v_fma_f32 v3, v15, v10, v3
	v_add_f32_e32 v10, v25, v2
	v_add_f32_e32 v11, v27, v3
	v_lshl_add_u64 v[6:7], v[6:7], 0, s[36:37]
	s_waitcnt vmcnt(60)
	v_cvt_pk_bf16_f32 v148, v8, v10
	v_cvt_pk_bf16_f32 v1, v9, v11
	v_mul_f32_e32 v2, v13, v9
	v_mul_f32_e32 v3, v12, v9
	global_store_dword v[6:7], v148, off
	global_store_dword v[6:7], v1, off offset:128
	v_fma_f32 v2, v12, v8, -v2
	v_fma_f32 v3, v13, v8, v3
	v_add_f32_e32 v8, v28, v2
	v_add_f32_e32 v9, v30, v3
	v_mul_f32_e32 v2, v15, v11
	v_mul_f32_e32 v3, v14, v11
	v_fma_f32 v2, v14, v10, -v2
	v_fma_f32 v3, v15, v10, v3
	v_add_f32_e32 v10, v29, v2
	v_add_f32_e32 v11, v31, v3
	v_lshl_add_u64 v[6:7], v[6:7], 0, s[36:37]
	s_waitcnt vmcnt(60)
	v_cvt_pk_bf16_f32 v148, v8, v10
	v_cvt_pk_bf16_f32 v1, v9, v11
	v_mul_f32_e32 v2, v13, v9
	v_mul_f32_e32 v3, v12, v9
	global_store_dword v[6:7], v148, off
	global_store_dword v[6:7], v1, off offset:128
	v_fma_f32 v2, v12, v8, -v2
	v_fma_f32 v3, v13, v8, v3
	v_add_f32_e32 v8, v32, v2
	v_add_f32_e32 v9, v34, v3
	v_mul_f32_e32 v2, v15, v11
	v_mul_f32_e32 v3, v14, v11
	v_fma_f32 v2, v14, v10, -v2
	v_fma_f32 v3, v15, v10, v3
	v_add_f32_e32 v10, v33, v2
	v_add_f32_e32 v11, v35, v3
	v_lshl_add_u64 v[6:7], v[6:7], 0, s[36:37]
	s_waitcnt vmcnt(60)
	v_cvt_pk_bf16_f32 v148, v8, v10
	v_cvt_pk_bf16_f32 v1, v9, v11
	v_mul_f32_e32 v2, v13, v9
	v_mul_f32_e32 v3, v12, v9
	global_store_dword v[6:7], v148, off
	global_store_dword v[6:7], v1, off offset:128
	v_fma_f32 v2, v12, v8, -v2
	v_fma_f32 v3, v13, v8, v3
	v_add_f32_e32 v8, v36, v2
	v_add_f32_e32 v9, v38, v3
	v_mul_f32_e32 v2, v15, v11
	v_mul_f32_e32 v3, v14, v11
	v_fma_f32 v2, v14, v10, -v2
	v_fma_f32 v3, v15, v10, v3
	v_add_f32_e32 v10, v37, v2
	v_add_f32_e32 v11, v39, v3
	v_lshl_add_u64 v[6:7], v[6:7], 0, s[36:37]
	s_waitcnt vmcnt(60)
	v_cvt_pk_bf16_f32 v148, v8, v10
	v_cvt_pk_bf16_f32 v1, v9, v11
	v_mul_f32_e32 v2, v13, v9
	v_mul_f32_e32 v3, v12, v9
	global_store_dword v[6:7], v148, off
	global_store_dword v[6:7], v1, off offset:128
	v_fma_f32 v2, v12, v8, -v2
	v_fma_f32 v3, v13, v8, v3
	v_add_f32_e32 v8, v40, v2
	v_add_f32_e32 v9, v42, v3
	v_mul_f32_e32 v2, v15, v11
	v_mul_f32_e32 v3, v14, v11
	v_fma_f32 v2, v14, v10, -v2
	v_fma_f32 v3, v15, v10, v3
	v_add_f32_e32 v10, v41, v2
	v_add_f32_e32 v11, v43, v3
	v_lshl_add_u64 v[6:7], v[6:7], 0, s[36:37]
	s_waitcnt vmcnt(60)
	v_cvt_pk_bf16_f32 v148, v8, v10
	v_cvt_pk_bf16_f32 v1, v9, v11
	v_mul_f32_e32 v2, v13, v9
	v_mul_f32_e32 v3, v12, v9
	global_store_dword v[6:7], v148, off
	global_store_dword v[6:7], v1, off offset:128
	v_fma_f32 v2, v12, v8, -v2
	v_fma_f32 v3, v13, v8, v3
	v_add_f32_e32 v8, v44, v2
	v_add_f32_e32 v9, v46, v3
	v_mul_f32_e32 v2, v15, v11
	v_mul_f32_e32 v3, v14, v11
	v_fma_f32 v2, v14, v10, -v2
	v_fma_f32 v3, v15, v10, v3
	v_add_f32_e32 v10, v45, v2
	v_add_f32_e32 v11, v47, v3
	v_lshl_add_u64 v[6:7], v[6:7], 0, s[36:37]
	s_waitcnt vmcnt(60)
	v_cvt_pk_bf16_f32 v148, v8, v10
	v_cvt_pk_bf16_f32 v1, v9, v11
	v_mul_f32_e32 v2, v13, v9
	v_mul_f32_e32 v3, v12, v9
	global_store_dword v[6:7], v148, off
	global_store_dword v[6:7], v1, off offset:128
	v_fma_f32 v2, v12, v8, -v2
	v_fma_f32 v3, v13, v8, v3
	v_add_f32_e32 v8, v48, v2
	v_add_f32_e32 v9, v50, v3
	v_mul_f32_e32 v2, v15, v11
	v_mul_f32_e32 v3, v14, v11
	v_fma_f32 v2, v14, v10, -v2
	v_fma_f32 v3, v15, v10, v3
	v_add_f32_e32 v10, v49, v2
	v_add_f32_e32 v11, v51, v3
	v_lshl_add_u64 v[6:7], v[6:7], 0, s[36:37]
	s_waitcnt vmcnt(60)
	v_cvt_pk_bf16_f32 v148, v8, v10
	v_cvt_pk_bf16_f32 v1, v9, v11
	v_mul_f32_e32 v2, v13, v9
	v_mul_f32_e32 v3, v12, v9
	global_store_dword v[6:7], v148, off
	global_store_dword v[6:7], v1, off offset:128
	v_fma_f32 v2, v12, v8, -v2
	v_fma_f32 v3, v13, v8, v3
	v_add_f32_e32 v8, v52, v2
	v_add_f32_e32 v9, v54, v3
	v_mul_f32_e32 v2, v15, v11
	v_mul_f32_e32 v3, v14, v11
	v_fma_f32 v2, v14, v10, -v2
	v_fma_f32 v3, v15, v10, v3
	v_add_f32_e32 v10, v53, v2
	v_add_f32_e32 v11, v55, v3
	v_lshl_add_u64 v[6:7], v[6:7], 0, s[36:37]
	s_waitcnt vmcnt(60)
; __device__ __forceinline__ unsigned f2bf(float f) { unsigned u = __builtin_bit_cast(unsigned, f); return (u + 0x7fffu + ((u >> 16) & 1u)) >> 16; }
; __device__ __forceinline__ void ssm_scan(Frame& F, int g, int pm) {
;     ...
;     for (int k0 = 0; k0 < NCH; k0 += 32) {
;         float sr[32], si[32];
; #pragma unroll
;         for (int q = 0; q < 32; ++q) { const int k = d == 0 ? k0 + q : NCH - 1 - (k0 + q); sr[q] = ST[(size_t)k * 256]; si[q] = ST[(size_t)k * 256 + 64]; }
; #pragma unroll
;         for (int q = 0; q < 32; ++q) { const int k = d == 0 ? k0 + q : NCH - 1 - (k0 + q);
;             AS[(size_t)k * KTO] = (bf16)f2bf(xr); AS[(size_t)k * KTO + 64] = (bf16)f2bf(xi);
;             const float nr = ar * xr - ai * xi + sr[q], ni = ar * xi + ai * xr + si[q]; xr = nr; xi = ni; }
	v_cvt_pk_bf16_f32 v148, v8, v10
	v_cvt_pk_bf16_f32 v1, v9, v11
	v_mul_f32_e32 v2, v13, v9
	v_mul_f32_e32 v3, v12, v9
	global_store_dword v[6:7], v148, off
	global_store_dword v[6:7], v1, off offset:128
	v_fma_f32 v2, v12, v8, -v2
	v_fma_f32 v3, v13, v8, v3
	v_add_f32_e32 v8, v56, v2
	v_add_f32_e32 v9, v58, v3
	v_mul_f32_e32 v2, v15, v11
	v_mul_f32_e32 v3, v14, v11
	v_fma_f32 v2, v14, v10, -v2
	v_fma_f32 v3, v15, v10, v3
	v_add_f32_e32 v10, v57, v2
	v_add_f32_e32 v11, v59, v3
	v_lshl_add_u64 v[6:7], v[6:7], 0, s[36:37]
	s_waitcnt vmcnt(60)
	v_cvt_pk_bf16_f32 v148, v8, v10
	v_cvt_pk_bf16_f32 v1, v9, v11
	v_mul_f32_e32 v2, v13, v9
	v_mul_f32_e32 v3, v12, v9
	global_store_dword v[6:7], v148, off
	global_store_dword v[6:7], v1, off offset:128
	v_fma_f32 v2, v12, v8, -v2
	v_fma_f32 v3, v13, v8, v3
	v_add_f32_e32 v8, v60, v2
	v_add_f32_e32 v9, v62, v3
	v_mul_f32_e32 v2, v15, v11
	v_mul_f32_e32 v3, v14, v11
	v_fma_f32 v2, v14, v10, -v2
	v_fma_f32 v3, v15, v10, v3
	v_add_f32_e32 v10, v61, v2
	v_add_f32_e32 v11, v63, v3
	v_lshl_add_u64 v[6:7], v[6:7], 0, s[36:37]
	s_waitcnt vmcnt(60)
	v_cvt_pk_bf16_f32 v148, v8, v10
	v_cvt_pk_bf16_f32 v1, v9, v11
	v_mul_f32_e32 v2, v13, v9
	v_mul_f32_e32 v3, v12, v9
	global_store_dword v[6:7], v148, off
	global_store_dword v[6:7], v1, off offset:128
	v_fma_f32 v2, v12, v8, -v2
	v_fma_f32 v3, v13, v8, v3
	v_add_f32_e32 v8, v64, v2
	v_add_f32_e32 v9, v66, v3
	v_mul_f32_e32 v2, v15, v11
	v_mul_f32_e32 v3, v14, v11
	v_fma_f32 v2, v14, v10, -v2
	v_fma_f32 v3, v15, v10, v3
	v_add_f32_e32 v10, v65, v2
	v_add_f32_e32 v11, v67, v3
	v_lshl_add_u64 v[6:7], v[6:7], 0, s[36:37]
	s_waitcnt vmcnt(60)
	v_cvt_pk_bf16_f32 v148, v8, v10
	v_cvt_pk_bf16_f32 v1, v9, v11
	v_mul_f32_e32 v2, v13, v9
	v_mul_f32_e32 v3, v12, v9
	global_store_dword v[6:7], v148, off
	global_store_dword v[6:7], v1, off offset:128
	v_fma_f32 v2, v12, v8, -v2
	v_fma_f32 v3, v13, v8, v3
	v_add_f32_e32 v8, v68, v2
	v_add_f32_e32 v9, v70, v3
	v_mul_f32_e32 v2, v15, v11
	v_mul_f32_e32 v3, v14, v11
	v_fma_f32 v2, v14, v10, -v2
	v_fma_f32 v3, v15, v10, v3
	v_add_f32_e32 v10, v69, v2
	v_add_f32_e32 v11, v71, v3
	v_lshl_add_u64 v[6:7], v[6:7], 0, s[36:37]
	s_waitcnt vmcnt(60)
	v_cvt_pk_bf16_f32 v148, v8, v10
	v_cvt_pk_bf16_f32 v1, v9, v11
	v_mul_f32_e32 v2, v13, v9
	v_mul_f32_e32 v3, v12, v9
	global_store_dword v[6:7], v148, off
	global_store_dword v[6:7], v1, off offset:128
	v_fma_f32 v2, v12, v8, -v2
	v_fma_f32 v3, v13, v8, v3
	v_add_f32_e32 v8, v72, v2
	v_add_f32_e32 v9, v74, v3
	v_mul_f32_e32 v2, v15, v11
	v_mul_f32_e32 v3, v14, v11
	v_fma_f32 v2, v14, v10, -v2
	v_fma_f32 v3, v15, v10, v3
	v_add_f32_e32 v10, v73, v2
	v_add_f32_e32 v11, v75, v3
	v_lshl_add_u64 v[6:7], v[6:7], 0, s[36:37]
	s_waitcnt vmcnt(60)
	v_cvt_pk_bf16_f32 v148, v8, v10
	v_cvt_pk_bf16_f32 v1, v9, v11
	v_mul_f32_e32 v2, v13, v9
	v_mul_f32_e32 v3, v12, v9
	global_store_dword v[6:7], v148, off
	global_store_dword v[6:7], v1, off offset:128
	v_fma_f32 v2, v12, v8, -v2
	v_fma_f32 v3, v13, v8, v3
	v_add_f32_e32 v8, v76, v2
	v_add_f32_e32 v9, v78, v3
	v_mul_f32_e32 v2, v15, v11
	v_mul_f32_e32 v3, v14, v11
	v_fma_f32 v2, v14, v10, -v2
	v_fma_f32 v3, v15, v10, v3
	v_add_f32_e32 v10, v77, v2
	v_add_f32_e32 v11, v79, v3
	v_lshl_add_u64 v[6:7], v[6:7], 0, s[36:37]
	s_waitcnt vmcnt(60)
	v_cvt_pk_bf16_f32 v148, v8, v10
	v_cvt_pk_bf16_f32 v1, v9, v11
	v_mul_f32_e32 v2, v13, v9
	v_mul_f32_e32 v3, v12, v9
	global_store_dword v[6:7], v148, off
	global_store_dword v[6:7], v1, off offset:128
	v_fma_f32 v2, v12, v8, -v2
	v_fma_f32 v3, v13, v8, v3
	v_add_f32_e32 v8, v80, v2
	v_add_f32_e32 v9, v82, v3
	v_mul_f32_e32 v2, v15, v11
	v_mul_f32_e32 v3, v14, v11
	v_fma_f32 v2, v14, v10, -v2
	v_fma_f32 v3, v15, v10, v3
	v_add_f32_e32 v10, v81, v2
	v_add_f32_e32 v11, v83, v3
	v_lshl_add_u64 v[6:7], v[6:7], 0, s[36:37]
	s_waitcnt vmcnt(60)
	v_cvt_pk_bf16_f32 v148, v8, v10
	v_cvt_pk_bf16_f32 v1, v9, v11
	v_mul_f32_e32 v2, v13, v9
	v_mul_f32_e32 v3, v12, v9
	global_store_dword v[6:7], v148, off
	global_store_dword v[6:7], v1, off offset:128
	v_fma_f32 v2, v12, v8, -v2
	v_fma_f32 v3, v13, v8, v3
	v_add_f32_e32 v8, v84, v2
	v_add_f32_e32 v9, v86, v3
	v_mul_f32_e32 v2, v15, v11
	v_mul_f32_e32 v3, v14, v11
	v_fma_f32 v2, v14, v10, -v2
	v_fma_f32 v3, v15, v10, v3
	v_add_f32_e32 v10, v85, v2
	v_add_f32_e32 v11, v87, v3
	v_lshl_add_u64 v[6:7], v[6:7], 0, s[36:37]
	s_waitcnt vmcnt(60)
	v_cvt_pk_bf16_f32 v148, v8, v10
	v_cvt_pk_bf16_f32 v1, v9, v11
	v_mul_f32_e32 v2, v13, v9
	v_mul_f32_e32 v3, v12, v9
	global_store_dword v[6:7], v148, off
	global_store_dword v[6:7], v1, off offset:128
	v_fma_f32 v2, v12, v8, -v2
	v_fma_f32 v3, v13, v8, v3
	v_add_f32_e32 v8, v88, v2
	v_add_f32_e32 v9, v90, v3
	v_mul_f32_e32 v2, v15, v11
	v_mul_f32_e32 v3, v14, v11
	v_fma_f32 v2, v14, v10, -v2
	v_fma_f32 v3, v15, v10, v3
	v_add_f32_e32 v10, v89, v2
	v_add_f32_e32 v11, v91, v3
	v_lshl_add_u64 v[6:7], v[6:7], 0, s[36:37]
	s_waitcnt vmcnt(60)
	v_cvt_pk_bf16_f32 v148, v8, v10
	v_cvt_pk_bf16_f32 v1, v9, v11
	v_mul_f32_e32 v2, v13, v9
	v_mul_f32_e32 v3, v12, v9
	global_store_dword v[6:7], v148, off
	global_store_dword v[6:7], v1, off offset:128
	v_fma_f32 v2, v12, v8, -v2
	v_fma_f32 v3, v13, v8, v3
	v_add_f32_e32 v8, v92, v2
	v_add_f32_e32 v9, v94, v3
	v_mul_f32_e32 v2, v15, v11
	v_mul_f32_e32 v3, v14, v11
	v_fma_f32 v2, v14, v10, -v2
	v_fma_f32 v3, v15, v10, v3
	v_add_f32_e32 v10, v93, v2
	v_add_f32_e32 v11, v95, v3
	v_lshl_add_u64 v[6:7], v[6:7], 0, s[36:37]
	s_waitcnt vmcnt(60)
; __device__ __forceinline__ unsigned f2bf(float f) { unsigned u = __builtin_bit_cast(unsigned, f); return (u + 0x7fffu + ((u >> 16) & 1u)) >> 16; }
; __device__ __forceinline__ void ssm_scan(Frame& F, int g, int pm) {
;     ...
;     for (int k0 = 0; k0 < NCH; k0 += 32) {
;         float sr[32], si[32];
; #pragma unroll
;         for (int q = 0; q < 32; ++q) { const int k = d == 0 ? k0 + q : NCH - 1 - (k0 + q); sr[q] = ST[(size_t)k * 256]; si[q] = ST[(size_t)k * 256 + 64]; }
; #pragma unroll
;         for (int q = 0; q < 32; ++q) { const int k = d == 0 ? k0 + q : NCH - 1 - (k0 + q);
;             AS[(size_t)k * KTO] = (bf16)f2bf(xr); AS[(size_t)k * KTO + 64] = (bf16)f2bf(xi);
;             const float nr = ar * xr - ai * xi + sr[q], ni = ar * xi + ai * xr + si[q]; xr = nr; xi = ni; }
;     }
; }
	v_cvt_pk_bf16_f32 v148, v8, v10
	v_cvt_pk_bf16_f32 v1, v9, v11
	v_mul_f32_e32 v2, v13, v9
	v_mul_f32_e32 v3, v12, v9
	global_store_dword v[6:7], v148, off
	global_store_dword v[6:7], v1, off offset:128
	v_fma_f32 v2, v12, v8, -v2
	v_fma_f32 v3, v13, v8, v3
	v_add_f32_e32 v8, v96, v2
	v_add_f32_e32 v9, v98, v3
	v_mul_f32_e32 v2, v15, v11
	v_mul_f32_e32 v3, v14, v11
	v_fma_f32 v2, v14, v10, -v2
	v_fma_f32 v3, v15, v10, v3
	v_add_f32_e32 v10, v97, v2
	v_add_f32_e32 v11, v99, v3
	v_lshl_add_u64 v[6:7], v[6:7], 0, s[36:37]
	s_waitcnt vmcnt(60)
	v_cvt_pk_bf16_f32 v148, v8, v10
	v_cvt_pk_bf16_f32 v1, v9, v11
	v_mul_f32_e32 v2, v13, v9
	v_mul_f32_e32 v3, v12, v9
	global_store_dword v[6:7], v148, off
	global_store_dword v[6:7], v1, off offset:128
	v_fma_f32 v2, v12, v8, -v2
	v_fma_f32 v3, v13, v8, v3
	v_add_f32_e32 v8, v100, v2
	v_add_f32_e32 v9, v102, v3
	v_mul_f32_e32 v2, v15, v11
	v_mul_f32_e32 v3, v14, v11
	v_fma_f32 v2, v14, v10, -v2
	v_fma_f32 v3, v15, v10, v3
	v_add_f32_e32 v10, v101, v2
	v_add_f32_e32 v11, v103, v3
	v_lshl_add_u64 v[6:7], v[6:7], 0, s[36:37]
	s_waitcnt vmcnt(60)
	v_cvt_pk_bf16_f32 v148, v8, v10
	v_cvt_pk_bf16_f32 v1, v9, v11
	v_mul_f32_e32 v2, v13, v9
	v_mul_f32_e32 v3, v12, v9
	global_store_dword v[6:7], v148, off
	global_store_dword v[6:7], v1, off offset:128
	v_fma_f32 v2, v12, v8, -v2
	v_fma_f32 v3, v13, v8, v3
	v_add_f32_e32 v8, v104, v2
	v_add_f32_e32 v9, v106, v3
	v_mul_f32_e32 v2, v15, v11
	v_mul_f32_e32 v3, v14, v11
	v_fma_f32 v2, v14, v10, -v2
	v_fma_f32 v3, v15, v10, v3
	v_add_f32_e32 v10, v105, v2
	v_add_f32_e32 v11, v107, v3
	v_lshl_add_u64 v[6:7], v[6:7], 0, s[36:37]
	s_waitcnt vmcnt(60)
	v_cvt_pk_bf16_f32 v148, v8, v10
	v_cvt_pk_bf16_f32 v1, v9, v11
	v_mul_f32_e32 v2, v13, v9
	v_mul_f32_e32 v3, v12, v9
	global_store_dword v[6:7], v148, off
	global_store_dword v[6:7], v1, off offset:128
	v_fma_f32 v2, v12, v8, -v2
	v_fma_f32 v3, v13, v8, v3
	v_add_f32_e32 v8, v108, v2
	v_add_f32_e32 v9, v110, v3
	v_mul_f32_e32 v2, v15, v11
	v_mul_f32_e32 v3, v14, v11
	v_fma_f32 v2, v14, v10, -v2
	v_fma_f32 v3, v15, v10, v3
	v_add_f32_e32 v10, v109, v2
	v_add_f32_e32 v11, v111, v3
	v_lshl_add_u64 v[6:7], v[6:7], 0, s[36:37]
	s_waitcnt vmcnt(60)
	v_cvt_pk_bf16_f32 v148, v8, v10
	v_cvt_pk_bf16_f32 v1, v9, v11
	v_mul_f32_e32 v2, v13, v9
	v_mul_f32_e32 v3, v12, v9
	global_store_dword v[6:7], v148, off
	global_store_dword v[6:7], v1, off offset:128
	v_fma_f32 v2, v12, v8, -v2
	v_fma_f32 v3, v13, v8, v3
	v_add_f32_e32 v8, v112, v2
	v_add_f32_e32 v9, v114, v3
	v_mul_f32_e32 v2, v15, v11
	v_mul_f32_e32 v3, v14, v11
	v_fma_f32 v2, v14, v10, -v2
	v_fma_f32 v3, v15, v10, v3
	v_add_f32_e32 v10, v113, v2
	v_add_f32_e32 v11, v115, v3
	v_lshl_add_u64 v[6:7], v[6:7], 0, s[36:37]
	s_waitcnt vmcnt(60)
	v_cvt_pk_bf16_f32 v148, v8, v10
	v_cvt_pk_bf16_f32 v1, v9, v11
	v_mul_f32_e32 v2, v13, v9
	v_mul_f32_e32 v3, v12, v9
	global_store_dword v[6:7], v148, off
	global_store_dword v[6:7], v1, off offset:128
	v_fma_f32 v2, v12, v8, -v2
	v_fma_f32 v3, v13, v8, v3
	v_add_f32_e32 v8, v116, v2
	v_add_f32_e32 v9, v118, v3
	v_mul_f32_e32 v2, v15, v11
	v_mul_f32_e32 v3, v14, v11
	v_fma_f32 v2, v14, v10, -v2
	v_fma_f32 v3, v15, v10, v3
	v_add_f32_e32 v10, v117, v2
	v_add_f32_e32 v11, v119, v3
	v_lshl_add_u64 v[6:7], v[6:7], 0, s[36:37]
	s_waitcnt vmcnt(60)
	v_cvt_pk_bf16_f32 v148, v8, v10
	v_cvt_pk_bf16_f32 v1, v9, v11
	v_mul_f32_e32 v2, v13, v9
	v_mul_f32_e32 v3, v12, v9
	global_store_dword v[6:7], v148, off
	global_store_dword v[6:7], v1, off offset:128
	v_fma_f32 v2, v12, v8, -v2
	v_fma_f32 v3, v13, v8, v3
	v_add_f32_e32 v8, v120, v2
	v_add_f32_e32 v9, v122, v3
	v_mul_f32_e32 v2, v15, v11
	v_mul_f32_e32 v3, v14, v11
	v_fma_f32 v2, v14, v10, -v2
	v_fma_f32 v3, v15, v10, v3
	v_add_f32_e32 v10, v121, v2
	v_add_f32_e32 v11, v123, v3
	v_lshl_add_u64 v[6:7], v[6:7], 0, s[36:37]
	s_waitcnt vmcnt(60)
	v_cvt_pk_bf16_f32 v148, v8, v10
	v_cvt_pk_bf16_f32 v1, v9, v11
	v_mul_f32_e32 v2, v13, v9
	v_mul_f32_e32 v3, v12, v9
	global_store_dword v[6:7], v148, off
	global_store_dword v[6:7], v1, off offset:128
	v_fma_f32 v2, v12, v8, -v2
	v_fma_f32 v3, v13, v8, v3
	v_add_f32_e32 v8, v124, v2
	v_add_f32_e32 v9, v126, v3
	v_mul_f32_e32 v2, v15, v11
	v_mul_f32_e32 v3, v14, v11
	v_fma_f32 v2, v14, v10, -v2
	v_fma_f32 v3, v15, v10, v3
	v_add_f32_e32 v10, v125, v2
	v_add_f32_e32 v11, v127, v3
	v_lshl_add_u64 v[6:7], v[6:7], 0, s[36:37]
	s_waitcnt vmcnt(60)
	v_cvt_pk_bf16_f32 v148, v8, v10
	v_cvt_pk_bf16_f32 v1, v9, v11
	v_mul_f32_e32 v2, v13, v9
	v_mul_f32_e32 v3, v12, v9
	global_store_dword v[6:7], v148, off
	global_store_dword v[6:7], v1, off offset:128
	v_fma_f32 v2, v12, v8, -v2
	v_fma_f32 v3, v13, v8, v3
	v_add_f32_e32 v8, v132, v2
	v_add_f32_e32 v9, v134, v3
	v_mul_f32_e32 v2, v15, v11
	v_mul_f32_e32 v3, v14, v11
	v_fma_f32 v2, v14, v10, -v2
	v_fma_f32 v3, v15, v10, v3
	v_add_f32_e32 v10, v133, v2
	v_add_f32_e32 v11, v135, v3
	v_lshl_add_u64 v[6:7], v[6:7], 0, s[36:37]
	s_waitcnt vmcnt(60)
	v_cvt_pk_bf16_f32 v148, v8, v10
	v_cvt_pk_bf16_f32 v1, v9, v11
	v_mul_f32_e32 v2, v13, v9
	v_mul_f32_e32 v3, v12, v9
	global_store_dword v[6:7], v148, off
	global_store_dword v[6:7], v1, off offset:128
	v_fma_f32 v2, v12, v8, -v2
	v_fma_f32 v3, v13, v8, v3
	v_add_f32_e32 v8, v136, v2
	v_add_f32_e32 v9, v138, v3
	v_mul_f32_e32 v2, v15, v11
	v_mul_f32_e32 v3, v14, v11
	v_fma_f32 v2, v14, v10, -v2
	v_fma_f32 v3, v15, v10, v3
	v_add_f32_e32 v10, v137, v2
	v_add_f32_e32 v11, v139, v3
	v_lshl_add_u64 v[6:7], v[6:7], 0, s[36:37]
	s_waitcnt vmcnt(60)
	v_cvt_pk_bf16_f32 v148, v8, v10
	v_cvt_pk_bf16_f32 v1, v9, v11
	v_mul_f32_e32 v2, v13, v9
	v_mul_f32_e32 v3, v12, v9
	global_store_dword v[6:7], v148, off
	global_store_dword v[6:7], v1, off offset:128
	v_fma_f32 v2, v12, v8, -v2
	v_fma_f32 v3, v13, v8, v3
	v_add_f32_e32 v8, v140, v2
	v_add_f32_e32 v9, v142, v3
	v_mul_f32_e32 v2, v15, v11
	v_mul_f32_e32 v3, v14, v11
	v_fma_f32 v2, v14, v10, -v2
	v_fma_f32 v3, v15, v10, v3
	v_add_f32_e32 v10, v141, v2
	v_add_f32_e32 v11, v143, v3
	v_lshl_add_u64 v[6:7], v[6:7], 0, s[36:37]
	s_waitcnt vmcnt(60)
	v_cvt_pk_bf16_f32 v148, v8, v10
	v_cvt_pk_bf16_f32 v1, v9, v11
	v_mul_f32_e32 v2, v13, v9
	v_mul_f32_e32 v3, v12, v9
	global_store_dword v[6:7], v148, off
	global_store_dword v[6:7], v1, off offset:128
	v_fma_f32 v2, v12, v8, -v2
	v_fma_f32 v3, v13, v8, v3
	v_add_f32_e32 v8, v144, v2
	v_add_f32_e32 v9, v146, v3
	v_mul_f32_e32 v2, v15, v11
	v_mul_f32_e32 v3, v14, v11
	v_fma_f32 v2, v14, v10, -v2
	v_fma_f32 v3, v15, v10, v3
	v_add_f32_e32 v10, v145, v2
	v_add_f32_e32 v11, v147, v3
.Lscan_done:
	v_readlane_b32 s90, v250, 1
	s_mov_b32 s87, s64
	s_mov_b32 s88, s65
	s_mov_b32 s89, s94
	v_readlane_b32 s64, v250, 0
	v_readlane_b32 s91, v250, 2
